# v4relax
# baseline (speedup 1.0000x reference)
; __device__ __forceinline__ u16 f2bf(float x) { return (u16)(cvtpk(x, x) & 0xffffu); }
; #define UNR _Pragma("unroll")
; template <int EPI, int lda, int ldb, int N, int K>
; __device__ __forceinline__ void gemm_phase(const u16* __restrict__ A, const u16* __restrict__ Bt, const GemmEpi ep, int wv) {
;     ...
;     if constexpr (EPI == EPI_SWIGLU) {
;       u16* out = reinterpret_cast<u16*>(ep.out0);
;       UNR for (int ai = 0; ai < 2; ++ai) UNR for (int m = 0; m < 4; ++m) {
;         const int rl0 = ai * HALF + wr * 64 + m * 16 + fq * 4;
;         const f32x4 r4 = *reinterpret_cast<const f32x4*>(lrs + rl0);
;         UNR for (int j = 0; j < 4; ++j) {
;           const int row = brow + rl0 + j;
;           const float rs = r4[j], ce = -1.4426950408889634f * rs, r2 = rs * rs;
;           UNR for (int n = 0; n < 2; ++n) {
;             const int col = (bcol >> 1) + wc * 32 + n * 16 + fr;
;             const float g = acc[ai][0][m][n][j], u = acc[ai][1][m][n][j];
;             const float sg = __builtin_amdgcn_rcpf(1.f + __builtin_amdgcn_exp2f(ce * g));
;             out[(size_t)row * ep.ldc + col] = f2bf((g * u) * (r2 * sg));
;           }
;         }
;       }
.LBB0_60:
	s_or_b64 exec, exec, s[48:49]
	v_and_b32_e32 v135, 15, v130
	v_lshrrev_b32_e32 v149, 8, v130
	v_lshl_add_u32 v135, v149, 6, v135
	v_lshlrev_b32_e32 v133, 2, v135
	v_add_u32_e32 v133, 0x20000, v133
	ds_read_b32 v150, v133 offset:0
	ds_read_b32 v151, v133 offset:64
	ds_read_b32 v152, v133 offset:128
	ds_read_b32 v153, v133 offset:192
	v_add_u32_e32 v135, s38, v135
	v_mul_u32_u24_e32 v132, 0x2b00, v135
	v_bfe_u32 v149, v130, 6, 2
	v_lshlrev_b32_e32 v149, 5, v149
	v_bfe_u32 v135, v130, 4, 1
	v_lshl_add_u32 v149, v135, 4, v149
	v_bfe_u32 v135, v130, 5, 1
	v_lshl_add_u32 v149, v135, 3, v149
	v_lshrrev_b32_e64 v135, 1, s39
	v_add_u32_e32 v149, v135, v149
	v_lshl_add_u32 v132, v149, 1, v132
	s_waitcnt lgkmcnt(0)
	v_mul_f32_e32 v135, 0xbfb8aa3b, v150
	v_mul_f32_e32 v149, v150, v150
	ds_read_b32 v150, v133 offset:512
	v_mul_f32_e32 v124, v116, v124
	v_mul_f32_e32 v125, v117, v125
	v_mul_f32_e32 v116, v135, v116
	v_mul_f32_e32 v117, v135, v117
	v_exp_f32_e32 v116, v116
	v_exp_f32_e32 v117, v117
	v_add_f32_e32 v116, 1.0, v116
	v_add_f32_e32 v117, 1.0, v117
	v_rcp_f32_e32 v116, v116
	v_rcp_f32_e32 v117, v117
	v_mul_f32_e32 v116, v149, v116
	v_mul_f32_e32 v117, v149, v117
	v_mul_f32_e32 v124, v124, v116
	v_mul_f32_e32 v125, v125, v117
	v_cvt_pk_bf16_f32 v116, v124, v125
	v_mul_f32_e32 v126, v118, v126
	v_mul_f32_e32 v127, v119, v127
	v_mul_f32_e32 v118, v135, v118
	v_mul_f32_e32 v119, v135, v119
	v_exp_f32_e32 v118, v118
	v_exp_f32_e32 v119, v119
	v_add_f32_e32 v118, 1.0, v118
	v_add_f32_e32 v119, 1.0, v119
	v_rcp_f32_e32 v118, v118
	v_rcp_f32_e32 v119, v119
	v_mul_f32_e32 v118, v149, v118
	v_mul_f32_e32 v119, v149, v119
	v_mul_f32_e32 v126, v126, v118
	v_mul_f32_e32 v127, v127, v119
	v_cvt_pk_bf16_f32 v117, v126, v127
	v_mul_f32_e32 v120, v112, v120
	v_mul_f32_e32 v121, v113, v121
	v_mul_f32_e32 v112, v135, v112
	v_mul_f32_e32 v113, v135, v113
	v_exp_f32_e32 v112, v112
	v_exp_f32_e32 v113, v113
	v_add_f32_e32 v112, 1.0, v112
	v_add_f32_e32 v113, 1.0, v113
	v_rcp_f32_e32 v112, v112
	v_rcp_f32_e32 v113, v113
	v_mul_f32_e32 v112, v149, v112
	v_mul_f32_e32 v113, v149, v113
	v_mul_f32_e32 v120, v120, v112
	v_mul_f32_e32 v121, v121, v113
	v_cvt_pk_bf16_f32 v118, v120, v121
	v_mul_f32_e32 v122, v114, v122
	v_mul_f32_e32 v123, v115, v123
	v_mul_f32_e32 v114, v135, v114
	v_mul_f32_e32 v115, v135, v115
	v_exp_f32_e32 v114, v114
	v_exp_f32_e32 v115, v115
	v_add_f32_e32 v114, 1.0, v114
	v_add_f32_e32 v115, 1.0, v115
	v_rcp_f32_e32 v114, v114
	v_rcp_f32_e32 v115, v115
	v_mul_f32_e32 v114, v149, v114
	v_mul_f32_e32 v115, v149, v115
	v_mul_f32_e32 v122, v122, v114
	v_mul_f32_e32 v123, v123, v115
	v_cvt_pk_bf16_f32 v119, v122, v123
	s_nop 1
	v_permlane16_swap_b32_e32 v116, v118
	v_permlane16_swap_b32_e32 v117, v119
	global_store_dwordx4 v132, v[116:119], s[10:11]
	v_add_u32_e32 v134, 0x2b000, v132
	v_mul_f32_e32 v135, 0xbfb8aa3b, v151
	v_mul_f32_e32 v149, v151, v151
	ds_read_b32 v151, v133 offset:576
	v_mul_f32_e32 v108, v100, v108
	v_mul_f32_e32 v109, v101, v109
	v_mul_f32_e32 v100, v135, v100
	v_mul_f32_e32 v101, v135, v101
	v_exp_f32_e32 v100, v100
	v_exp_f32_e32 v101, v101
	v_add_f32_e32 v100, 1.0, v100
	v_add_f32_e32 v101, 1.0, v101
	v_rcp_f32_e32 v100, v100
	v_rcp_f32_e32 v101, v101
	v_mul_f32_e32 v100, v149, v100
	v_mul_f32_e32 v101, v149, v101
	v_mul_f32_e32 v108, v108, v100
	v_mul_f32_e32 v109, v109, v101
	v_cvt_pk_bf16_f32 v100, v108, v109
	v_mul_f32_e32 v110, v102, v110
	v_mul_f32_e32 v111, v103, v111
	v_mul_f32_e32 v102, v135, v102
	v_mul_f32_e32 v103, v135, v103
	v_exp_f32_e32 v102, v102
	v_exp_f32_e32 v103, v103
	v_add_f32_e32 v102, 1.0, v102
	v_add_f32_e32 v103, 1.0, v103
	v_rcp_f32_e32 v102, v102
	v_rcp_f32_e32 v103, v103
	v_mul_f32_e32 v102, v149, v102
	v_mul_f32_e32 v103, v149, v103
	v_mul_f32_e32 v110, v110, v102
	v_mul_f32_e32 v111, v111, v103
	v_cvt_pk_bf16_f32 v101, v110, v111
	v_mul_f32_e32 v104, v96, v104
	v_mul_f32_e32 v105, v97, v105
	v_mul_f32_e32 v96, v135, v96
	v_mul_f32_e32 v97, v135, v97
	v_exp_f32_e32 v96, v96
	v_exp_f32_e32 v97, v97
	v_add_f32_e32 v96, 1.0, v96
	v_add_f32_e32 v97, 1.0, v97
	v_rcp_f32_e32 v96, v96
	v_rcp_f32_e32 v97, v97
	v_mul_f32_e32 v96, v149, v96
	v_mul_f32_e32 v97, v149, v97
	v_mul_f32_e32 v104, v104, v96
	v_mul_f32_e32 v105, v105, v97
	v_cvt_pk_bf16_f32 v102, v104, v105
	v_mul_f32_e32 v106, v98, v106
	v_mul_f32_e32 v107, v99, v107
	v_mul_f32_e32 v98, v135, v98
	v_mul_f32_e32 v99, v135, v99
	v_exp_f32_e32 v98, v98
	v_exp_f32_e32 v99, v99
	v_add_f32_e32 v98, 1.0, v98
	v_add_f32_e32 v99, 1.0, v99
	v_rcp_f32_e32 v98, v98
	v_rcp_f32_e32 v99, v99
	v_mul_f32_e32 v98, v149, v98
	v_mul_f32_e32 v99, v149, v99
	v_mul_f32_e32 v106, v106, v98
	v_mul_f32_e32 v107, v107, v99
	v_cvt_pk_bf16_f32 v103, v106, v107
	s_nop 1
	v_permlane16_swap_b32_e32 v100, v102
	v_permlane16_swap_b32_e32 v101, v103
	global_store_dwordx4 v134, v[100:103], s[10:11]
	v_add_u32_e32 v134, 0x56000, v132
	v_mul_f32_e32 v135, 0xbfb8aa3b, v152
	v_mul_f32_e32 v149, v152, v152
	ds_read_b32 v152, v133 offset:640
	v_mul_f32_e32 v92, v84, v92
	v_mul_f32_e32 v93, v85, v93
	v_mul_f32_e32 v84, v135, v84
	v_mul_f32_e32 v85, v135, v85
	v_exp_f32_e32 v84, v84
	v_exp_f32_e32 v85, v85
	v_add_f32_e32 v84, 1.0, v84
	v_add_f32_e32 v85, 1.0, v85
	v_rcp_f32_e32 v84, v84
	v_rcp_f32_e32 v85, v85
	v_mul_f32_e32 v84, v149, v84
	v_mul_f32_e32 v85, v149, v85
	v_mul_f32_e32 v92, v92, v84
	v_mul_f32_e32 v93, v93, v85
	v_cvt_pk_bf16_f32 v84, v92, v93
	v_mul_f32_e32 v94, v86, v94
	v_mul_f32_e32 v95, v87, v95
	v_mul_f32_e32 v86, v135, v86
	v_mul_f32_e32 v87, v135, v87
	v_exp_f32_e32 v86, v86
	v_exp_f32_e32 v87, v87
	v_add_f32_e32 v86, 1.0, v86
	v_add_f32_e32 v87, 1.0, v87
; __device__ __forceinline__ u16 f2bf(float x) { return (u16)(cvtpk(x, x) & 0xffffu); }
; #define UNR _Pragma("unroll")
; template <int EPI, int lda, int ldb, int N, int K>
; __device__ __forceinline__ void gemm_phase(const u16* __restrict__ A, const u16* __restrict__ Bt, const GemmEpi ep, int wv) {
;     ...
;     if constexpr (EPI == EPI_SWIGLU) {
;       u16* out = reinterpret_cast<u16*>(ep.out0);
;       UNR for (int ai = 0; ai < 2; ++ai) UNR for (int m = 0; m < 4; ++m) {
;         const int rl0 = ai * HALF + wr * 64 + m * 16 + fq * 4;
;         const f32x4 r4 = *reinterpret_cast<const f32x4*>(lrs + rl0);
;         UNR for (int j = 0; j < 4; ++j) {
;           const int row = brow + rl0 + j;
;           const float rs = r4[j], ce = -1.4426950408889634f * rs, r2 = rs * rs;
;           UNR for (int n = 0; n < 2; ++n) {
;             const int col = (bcol >> 1) + wc * 32 + n * 16 + fr;
;             const float g = acc[ai][0][m][n][j], u = acc[ai][1][m][n][j];
;             const float sg = __builtin_amdgcn_rcpf(1.f + __builtin_amdgcn_exp2f(ce * g));
;             out[(size_t)row * ep.ldc + col] = f2bf((g * u) * (r2 * sg));
;           }
;         }
;       }
	v_rcp_f32_e32 v86, v86
	v_rcp_f32_e32 v87, v87
	v_mul_f32_e32 v86, v149, v86
	v_mul_f32_e32 v87, v149, v87
	v_mul_f32_e32 v94, v94, v86
	v_mul_f32_e32 v95, v95, v87
	v_cvt_pk_bf16_f32 v85, v94, v95
	v_mul_f32_e32 v88, v80, v88
	v_mul_f32_e32 v89, v81, v89
	v_mul_f32_e32 v80, v135, v80
	v_mul_f32_e32 v81, v135, v81
	v_exp_f32_e32 v80, v80
	v_exp_f32_e32 v81, v81
	v_add_f32_e32 v80, 1.0, v80
	v_add_f32_e32 v81, 1.0, v81
	v_rcp_f32_e32 v80, v80
	v_rcp_f32_e32 v81, v81
	v_mul_f32_e32 v80, v149, v80
	v_mul_f32_e32 v81, v149, v81
	v_mul_f32_e32 v88, v88, v80
	v_mul_f32_e32 v89, v89, v81
	v_cvt_pk_bf16_f32 v86, v88, v89
	v_mul_f32_e32 v90, v82, v90
	v_mul_f32_e32 v91, v83, v91
	v_mul_f32_e32 v82, v135, v82
	v_mul_f32_e32 v83, v135, v83
	v_exp_f32_e32 v82, v82
	v_exp_f32_e32 v83, v83
	v_add_f32_e32 v82, 1.0, v82
	v_add_f32_e32 v83, 1.0, v83
	v_rcp_f32_e32 v82, v82
	v_rcp_f32_e32 v83, v83
	v_mul_f32_e32 v82, v149, v82
	v_mul_f32_e32 v83, v149, v83
	v_mul_f32_e32 v90, v90, v82
	v_mul_f32_e32 v91, v91, v83
	v_cvt_pk_bf16_f32 v87, v90, v91
	s_nop 1
	v_permlane16_swap_b32_e32 v84, v86
	v_permlane16_swap_b32_e32 v85, v87
	global_store_dwordx4 v134, v[84:87], s[10:11]
	v_add_u32_e32 v134, 0x81000, v132
	v_mul_f32_e32 v135, 0xbfb8aa3b, v153
	v_mul_f32_e32 v149, v153, v153
	ds_read_b32 v153, v133 offset:704
	v_mul_f32_e32 v76, v68, v76
	v_mul_f32_e32 v77, v69, v77
	v_mul_f32_e32 v68, v135, v68
	v_mul_f32_e32 v69, v135, v69
	v_exp_f32_e32 v68, v68
	v_exp_f32_e32 v69, v69
	v_add_f32_e32 v68, 1.0, v68
	v_add_f32_e32 v69, 1.0, v69
	v_rcp_f32_e32 v68, v68
	v_rcp_f32_e32 v69, v69
	v_mul_f32_e32 v68, v149, v68
	v_mul_f32_e32 v69, v149, v69
	v_mul_f32_e32 v76, v76, v68
	v_mul_f32_e32 v77, v77, v69
	v_cvt_pk_bf16_f32 v68, v76, v77
	v_mul_f32_e32 v78, v70, v78
	v_mul_f32_e32 v79, v71, v79
	v_mul_f32_e32 v70, v135, v70
	v_mul_f32_e32 v71, v135, v71
	v_exp_f32_e32 v70, v70
	v_exp_f32_e32 v71, v71
	v_add_f32_e32 v70, 1.0, v70
	v_add_f32_e32 v71, 1.0, v71
	v_rcp_f32_e32 v70, v70
	v_rcp_f32_e32 v71, v71
	v_mul_f32_e32 v70, v149, v70
	v_mul_f32_e32 v71, v149, v71
	v_mul_f32_e32 v78, v78, v70
	v_mul_f32_e32 v79, v79, v71
	v_cvt_pk_bf16_f32 v69, v78, v79
	v_mul_f32_e32 v72, v64, v72
	v_mul_f32_e32 v73, v65, v73
	v_mul_f32_e32 v64, v135, v64
	v_mul_f32_e32 v65, v135, v65
	v_exp_f32_e32 v64, v64
	v_exp_f32_e32 v65, v65
	v_add_f32_e32 v64, 1.0, v64
	v_add_f32_e32 v65, 1.0, v65
	v_rcp_f32_e32 v64, v64
	v_rcp_f32_e32 v65, v65
	v_mul_f32_e32 v64, v149, v64
	v_mul_f32_e32 v65, v149, v65
	v_mul_f32_e32 v72, v72, v64
	v_mul_f32_e32 v73, v73, v65
	v_cvt_pk_bf16_f32 v70, v72, v73
	v_mul_f32_e32 v74, v66, v74
	v_mul_f32_e32 v75, v67, v75
	v_mul_f32_e32 v66, v135, v66
	v_mul_f32_e32 v67, v135, v67
	v_exp_f32_e32 v66, v66
	v_exp_f32_e32 v67, v67
	v_add_f32_e32 v66, 1.0, v66
	v_add_f32_e32 v67, 1.0, v67
	v_rcp_f32_e32 v66, v66
	v_rcp_f32_e32 v67, v67
	v_mul_f32_e32 v66, v149, v66
	v_mul_f32_e32 v67, v149, v67
	v_mul_f32_e32 v74, v74, v66
	v_mul_f32_e32 v75, v75, v67
	v_cvt_pk_bf16_f32 v71, v74, v75
	s_nop 1
	v_permlane16_swap_b32_e32 v68, v70
	v_permlane16_swap_b32_e32 v69, v71
	global_store_dwordx4 v134, v[68:71], s[10:11]
	s_waitcnt lgkmcnt(0)
	v_add_u32_e32 v134, 0x158000, v132
	v_mul_f32_e32 v135, 0xbfb8aa3b, v150
	v_mul_f32_e32 v149, v150, v150
	v_mul_f32_e32 v60, v52, v60
	v_mul_f32_e32 v61, v53, v61
	v_mul_f32_e32 v52, v135, v52
	v_mul_f32_e32 v53, v135, v53
	v_exp_f32_e32 v52, v52
	v_exp_f32_e32 v53, v53
	v_add_f32_e32 v52, 1.0, v52
	v_add_f32_e32 v53, 1.0, v53
	v_rcp_f32_e32 v52, v52
	v_rcp_f32_e32 v53, v53
	v_mul_f32_e32 v52, v149, v52
	v_mul_f32_e32 v53, v149, v53
	v_mul_f32_e32 v60, v60, v52
	v_mul_f32_e32 v61, v61, v53
	v_cvt_pk_bf16_f32 v52, v60, v61
	v_mul_f32_e32 v62, v54, v62
	v_mul_f32_e32 v63, v55, v63
	v_mul_f32_e32 v54, v135, v54
	v_mul_f32_e32 v55, v135, v55
	v_exp_f32_e32 v54, v54
	v_exp_f32_e32 v55, v55
	v_add_f32_e32 v54, 1.0, v54
	v_add_f32_e32 v55, 1.0, v55
	v_rcp_f32_e32 v54, v54
	v_rcp_f32_e32 v55, v55
	v_mul_f32_e32 v54, v149, v54
	v_mul_f32_e32 v55, v149, v55
	v_mul_f32_e32 v62, v62, v54
	v_mul_f32_e32 v63, v63, v55
	v_cvt_pk_bf16_f32 v53, v62, v63
	v_mul_f32_e32 v56, v48, v56
	v_mul_f32_e32 v57, v49, v57
	v_mul_f32_e32 v48, v135, v48
	v_mul_f32_e32 v49, v135, v49
	v_exp_f32_e32 v48, v48
	v_exp_f32_e32 v49, v49
	v_add_f32_e32 v48, 1.0, v48
	v_add_f32_e32 v49, 1.0, v49
	v_rcp_f32_e32 v48, v48
	v_rcp_f32_e32 v49, v49
	v_mul_f32_e32 v48, v149, v48
	v_mul_f32_e32 v49, v149, v49
	v_mul_f32_e32 v56, v56, v48
	v_mul_f32_e32 v57, v57, v49
	v_cvt_pk_bf16_f32 v54, v56, v57
	v_mul_f32_e32 v58, v50, v58
	v_mul_f32_e32 v59, v51, v59
	v_mul_f32_e32 v50, v135, v50
	v_mul_f32_e32 v51, v135, v51
	v_exp_f32_e32 v50, v50
	v_exp_f32_e32 v51, v51
	v_add_f32_e32 v50, 1.0, v50
	v_add_f32_e32 v51, 1.0, v51
	v_rcp_f32_e32 v50, v50
	v_rcp_f32_e32 v51, v51
	v_mul_f32_e32 v50, v149, v50
	v_mul_f32_e32 v51, v149, v51
	v_mul_f32_e32 v58, v58, v50
	v_mul_f32_e32 v59, v59, v51
	v_cvt_pk_bf16_f32 v55, v58, v59
	s_nop 1
	v_permlane16_swap_b32_e32 v52, v54
	v_permlane16_swap_b32_e32 v53, v55
	global_store_dwordx4 v134, v[52:55], s[10:11]
	v_add_u32_e32 v134, 0x183000, v132
	v_mul_f32_e32 v135, 0xbfb8aa3b, v151
	v_mul_f32_e32 v149, v151, v151
	v_mul_f32_e32 v44, v36, v44
	v_mul_f32_e32 v45, v37, v45
	v_mul_f32_e32 v36, v135, v36
	v_mul_f32_e32 v37, v135, v37
	v_exp_f32_e32 v36, v36
	v_exp_f32_e32 v37, v37
	v_add_f32_e32 v36, 1.0, v36
	v_add_f32_e32 v37, 1.0, v37
	v_rcp_f32_e32 v36, v36
	v_rcp_f32_e32 v37, v37
	v_mul_f32_e32 v36, v149, v36
	v_mul_f32_e32 v37, v149, v37
	v_mul_f32_e32 v44, v44, v36
	v_mul_f32_e32 v45, v45, v37
	v_cvt_pk_bf16_f32 v36, v44, v45
	v_mul_f32_e32 v46, v38, v46
; __device__ __forceinline__ u16 f2bf(float x) { return (u16)(cvtpk(x, x) & 0xffffu); }
; #define UNR _Pragma("unroll")
; #define WAIT_V(n) asm volatile("s_waitcnt vmcnt(" #n ")" ::: "memory")
; template <int EPI, int lda, int ldb, int N, int K>
; __device__ __forceinline__ void gemm_phase(const u16* __restrict__ A, const u16* __restrict__ Bt, const GemmEpi ep, int wv) {
;     ...
;     if constexpr (EPI == EPI_SWIGLU) {
;       u16* out = reinterpret_cast<u16*>(ep.out0);
;       UNR for (int ai = 0; ai < 2; ++ai) UNR for (int m = 0; m < 4; ++m) {
;         const int rl0 = ai * HALF + wr * 64 + m * 16 + fq * 4;
;         const f32x4 r4 = *reinterpret_cast<const f32x4*>(lrs + rl0);
;         UNR for (int j = 0; j < 4; ++j) {
;           const int row = brow + rl0 + j;
;           const float rs = r4[j], ce = -1.4426950408889634f * rs, r2 = rs * rs;
;           UNR for (int n = 0; n < 2; ++n) {
;             const int col = (bcol >> 1) + wc * 32 + n * 16 + fr;
;             const float g = acc[ai][0][m][n][j], u = acc[ai][1][m][n][j];
;             const float sg = __builtin_amdgcn_rcpf(1.f + __builtin_amdgcn_exp2f(ce * g));
;             out[(size_t)row * ep.ldc + col] = f2bf((g * u) * (r2 * sg));
;           }
;         }
;       }
;     ...
;     if constexpr (PF) {
;       WAIT_V(0);
;       __syncthreads();
;       if constexpr (CONS) { if (more && tidx < 256) { float sq = 0.f; UNR for (int pp = 0; pp < 8; ++pp) sq += nss[pp];
;         lrs[tidx] = rsqrtf(sq * (1.f / DM) + 1e-6f); } }
;       if (!more) break;
	v_mul_f32_e32 v47, v39, v47
	v_mul_f32_e32 v38, v135, v38
	v_mul_f32_e32 v39, v135, v39
	v_exp_f32_e32 v38, v38
	v_exp_f32_e32 v39, v39
	v_add_f32_e32 v38, 1.0, v38
	v_add_f32_e32 v39, 1.0, v39
	v_rcp_f32_e32 v38, v38
	v_rcp_f32_e32 v39, v39
	v_mul_f32_e32 v38, v149, v38
	v_mul_f32_e32 v39, v149, v39
	v_mul_f32_e32 v46, v46, v38
	v_mul_f32_e32 v47, v47, v39
	v_cvt_pk_bf16_f32 v37, v46, v47
	v_mul_f32_e32 v40, v32, v40
	v_mul_f32_e32 v41, v33, v41
	v_mul_f32_e32 v32, v135, v32
	v_mul_f32_e32 v33, v135, v33
	v_exp_f32_e32 v32, v32
	v_exp_f32_e32 v33, v33
	v_add_f32_e32 v32, 1.0, v32
	v_add_f32_e32 v33, 1.0, v33
	v_rcp_f32_e32 v32, v32
	v_rcp_f32_e32 v33, v33
	v_mul_f32_e32 v32, v149, v32
	v_mul_f32_e32 v33, v149, v33
	v_mul_f32_e32 v40, v40, v32
	v_mul_f32_e32 v41, v41, v33
	v_cvt_pk_bf16_f32 v38, v40, v41
	v_mul_f32_e32 v42, v34, v42
	v_mul_f32_e32 v43, v35, v43
	v_mul_f32_e32 v34, v135, v34
	v_mul_f32_e32 v35, v135, v35
	v_exp_f32_e32 v34, v34
	v_exp_f32_e32 v35, v35
	v_add_f32_e32 v34, 1.0, v34
	v_add_f32_e32 v35, 1.0, v35
	v_rcp_f32_e32 v34, v34
	v_rcp_f32_e32 v35, v35
	v_mul_f32_e32 v34, v149, v34
	v_mul_f32_e32 v35, v149, v35
	v_mul_f32_e32 v42, v42, v34
	v_mul_f32_e32 v43, v43, v35
	v_cvt_pk_bf16_f32 v39, v42, v43
	s_nop 1
	v_permlane16_swap_b32_e32 v36, v38
	v_permlane16_swap_b32_e32 v37, v39
	global_store_dwordx4 v134, v[36:39], s[10:11]
	v_add_u32_e32 v134, 0x1ae000, v132
	v_mul_f32_e32 v135, 0xbfb8aa3b, v152
	v_mul_f32_e32 v149, v152, v152
	v_mul_f32_e32 v28, v20, v28
	v_mul_f32_e32 v29, v21, v29
	v_mul_f32_e32 v20, v135, v20
	v_mul_f32_e32 v21, v135, v21
	v_exp_f32_e32 v20, v20
	v_exp_f32_e32 v21, v21
	v_add_f32_e32 v20, 1.0, v20
	v_add_f32_e32 v21, 1.0, v21
	v_rcp_f32_e32 v20, v20
	v_rcp_f32_e32 v21, v21
	v_mul_f32_e32 v20, v149, v20
	v_mul_f32_e32 v21, v149, v21
	v_mul_f32_e32 v28, v28, v20
	v_mul_f32_e32 v29, v29, v21
	v_cvt_pk_bf16_f32 v20, v28, v29
	v_mul_f32_e32 v30, v22, v30
	v_mul_f32_e32 v31, v23, v31
	v_mul_f32_e32 v22, v135, v22
	v_mul_f32_e32 v23, v135, v23
	v_exp_f32_e32 v22, v22
	v_exp_f32_e32 v23, v23
	v_add_f32_e32 v22, 1.0, v22
	v_add_f32_e32 v23, 1.0, v23
	v_rcp_f32_e32 v22, v22
	v_rcp_f32_e32 v23, v23
	v_mul_f32_e32 v22, v149, v22
	v_mul_f32_e32 v23, v149, v23
	v_mul_f32_e32 v30, v30, v22
	v_mul_f32_e32 v31, v31, v23
	v_cvt_pk_bf16_f32 v21, v30, v31
	v_mul_f32_e32 v24, v16, v24
	v_mul_f32_e32 v25, v17, v25
	v_mul_f32_e32 v16, v135, v16
	v_mul_f32_e32 v17, v135, v17
	v_exp_f32_e32 v16, v16
	v_exp_f32_e32 v17, v17
	v_add_f32_e32 v16, 1.0, v16
	v_add_f32_e32 v17, 1.0, v17
	v_rcp_f32_e32 v16, v16
	v_rcp_f32_e32 v17, v17
	v_mul_f32_e32 v16, v149, v16
	v_mul_f32_e32 v17, v149, v17
	v_mul_f32_e32 v24, v24, v16
	v_mul_f32_e32 v25, v25, v17
	v_cvt_pk_bf16_f32 v22, v24, v25
	v_mul_f32_e32 v26, v18, v26
	v_mul_f32_e32 v27, v19, v27
	v_mul_f32_e32 v18, v135, v18
	v_mul_f32_e32 v19, v135, v19
	v_exp_f32_e32 v18, v18
	v_exp_f32_e32 v19, v19
	v_add_f32_e32 v18, 1.0, v18
	v_add_f32_e32 v19, 1.0, v19
	v_rcp_f32_e32 v18, v18
	v_rcp_f32_e32 v19, v19
	v_mul_f32_e32 v18, v149, v18
	v_mul_f32_e32 v19, v149, v19
	v_mul_f32_e32 v26, v26, v18
	v_mul_f32_e32 v27, v27, v19
	v_cvt_pk_bf16_f32 v23, v26, v27
	s_nop 1
	v_permlane16_swap_b32_e32 v20, v22
	v_permlane16_swap_b32_e32 v21, v23
	global_store_dwordx4 v134, v[20:23], s[10:11]
	v_add_u32_e32 v134, 0x1d9000, v132
	v_mul_f32_e32 v135, 0xbfb8aa3b, v153
	v_mul_f32_e32 v149, v153, v153
	v_mul_f32_e32 v12, v4, v12
	v_mul_f32_e32 v13, v5, v13
	v_mul_f32_e32 v4, v135, v4
	v_mul_f32_e32 v5, v135, v5
	v_exp_f32_e32 v4, v4
	v_exp_f32_e32 v5, v5
	v_add_f32_e32 v4, 1.0, v4
	v_add_f32_e32 v5, 1.0, v5
	v_rcp_f32_e32 v4, v4
	v_rcp_f32_e32 v5, v5
	v_mul_f32_e32 v4, v149, v4
	v_mul_f32_e32 v5, v149, v5
	v_mul_f32_e32 v12, v12, v4
	v_mul_f32_e32 v13, v13, v5
	v_cvt_pk_bf16_f32 v4, v12, v13
	v_mul_f32_e32 v14, v6, v14
	v_mul_f32_e32 v15, v7, v15
	v_mul_f32_e32 v6, v135, v6
	v_mul_f32_e32 v7, v135, v7
	v_exp_f32_e32 v6, v6
	v_exp_f32_e32 v7, v7
	v_add_f32_e32 v6, 1.0, v6
	v_add_f32_e32 v7, 1.0, v7
	v_rcp_f32_e32 v6, v6
	v_rcp_f32_e32 v7, v7
	v_mul_f32_e32 v6, v149, v6
	v_mul_f32_e32 v7, v149, v7
	v_mul_f32_e32 v14, v14, v6
	v_mul_f32_e32 v15, v15, v7
	v_cvt_pk_bf16_f32 v5, v14, v15
	v_mul_f32_e32 v8, v0, v8
	v_mul_f32_e32 v9, v1, v9
	v_mul_f32_e32 v0, v135, v0
	v_mul_f32_e32 v1, v135, v1
	v_exp_f32_e32 v0, v0
	v_exp_f32_e32 v1, v1
	v_add_f32_e32 v0, 1.0, v0
	v_add_f32_e32 v1, 1.0, v1
	v_rcp_f32_e32 v0, v0
	v_rcp_f32_e32 v1, v1
	v_mul_f32_e32 v0, v149, v0
	v_mul_f32_e32 v1, v149, v1
	v_mul_f32_e32 v8, v8, v0
	v_mul_f32_e32 v9, v9, v1
	v_cvt_pk_bf16_f32 v6, v8, v9
	v_mul_f32_e32 v10, v2, v10
	v_mul_f32_e32 v11, v3, v11
	v_mul_f32_e32 v2, v135, v2
	v_mul_f32_e32 v3, v135, v3
	v_exp_f32_e32 v2, v2
	v_exp_f32_e32 v3, v3
	v_add_f32_e32 v2, 1.0, v2
	v_add_f32_e32 v3, 1.0, v3
	v_rcp_f32_e32 v2, v2
	v_rcp_f32_e32 v3, v3
	v_mul_f32_e32 v2, v149, v2
	v_mul_f32_e32 v3, v149, v3
	v_mul_f32_e32 v10, v10, v2
	v_mul_f32_e32 v11, v11, v3
	v_cvt_pk_bf16_f32 v7, v10, v11
	s_nop 1
	v_permlane16_swap_b32_e32 v4, v6
	v_permlane16_swap_b32_e32 v5, v7
	global_store_dwordx4 v134, v[4:7], s[10:11]
	s_waitcnt vmcnt(8)
	s_waitcnt vmcnt(8)
	v_add_f32_e32 v148, 0, v131
	s_barrier
	s_and_saveexec_b64 s[38:39], s[46:47]
	s_cbranch_execz .LBB0_49
	v_add_f32_e32 v0, v141, v148
	v_add_f32_e32 v0, v140, v0
	v_add_f32_e32 v0, v139, v0
	v_add_f32_e32 v0, v138, v0
	v_add_f32_e32 v0, v137, v0
	v_add_f32_e32 v0, v136, v0
	v_add_f32_e32 v0, v128, v0
	v_fmamk_f32 v0, v0, 0x3a000000, v143
	v_mul_f32_e32 v1, 0x4b800000, v0
	v_cmp_gt_f32_e32 vcc, s64, v0
	s_nop 1
	v_cndmask_b32_e32 v0, v0, v1, vcc
	v_rsq_f32_e32 v0, v0
	v_lshl_add_u32 v1, v130, 2, 0
	v_add_u32_e32 v1, 0x20000, v1
	v_mul_f32_e32 v2, 0x45800000, v0
	v_cndmask_b32_e32 v0, v0, v2, vcc
	ds_write_b32 v1, v0
	s_branch .LBB0_49

; #define UNR _Pragma("unroll")
; #define WAIT_V(n) asm volatile("s_waitcnt vmcnt(" #n ")" ::: "memory")
; template <int EPI, int lda, int ldb, int N, int K>
; __device__ __forceinline__ void gemm_phase(const u16* __restrict__ A, const u16* __restrict__ Bt, const GemmEpi ep, int wv) {
;     ...
;     if constexpr (PF) {
;       WAIT_V(0);
;       __syncthreads();
;       if constexpr (CONS) { if (more && tidx < 256) { float sq = 0.f; UNR for (int pp = 0; pp < 8; ++pp) sq += nss[pp];
;         lrs[tidx] = rsqrtf(sq * (1.f / DM) + 1e-6f); } }
;       if (!more) break;
;       tile = ntile; brow = nbrow; bcol = nbcol; pn = npn;
.LBB0_220:
	s_or_b64 exec, exec, s[46:47]
	s_waitcnt vmcnt(17)
	s_andn2_b64 vcc, exec, s[44:45]
	s_mov_b32 s53, s66
	s_mov_b32 s46, s67
	s_mov_b32 s14, s65
	s_waitcnt vmcnt(63) expcnt(7) lgkmcnt(15)
	s_barrier
	s_cbranch_vccz .LBB0_295

; #define UNR _Pragma("unroll")
; #define WAIT_V(n) asm volatile("s_waitcnt vmcnt(" #n ")" ::: "memory")
; template <int EPI, int lda, int ldb, int N, int K>
; __device__ __forceinline__ void gemm_phase(const u16* __restrict__ A, const u16* __restrict__ Bt, const GemmEpi ep, int wv) {
;     ...
;     if constexpr (PF) {
;       WAIT_V(0);
;       __syncthreads();
;       if constexpr (CONS) { if (more && tidx < 256) { float sq = 0.f; UNR for (int pp = 0; pp < 8; ++pp) sq += nss[pp];
;         lrs[tidx] = rsqrtf(sq * (1.f / DM) + 1e-6f); } }
;       if (!more) break;
;       tile = ntile; brow = nbrow; bcol = nbcol; pn = npn;
.LBB0_650:
	s_or_b64 exec, exec, s[58:59]
	s_waitcnt vmcnt(17)
	s_andn2_b64 vcc, exec, s[52:53]
	s_mov_b32 s64, s73
	s_mov_b32 s58, s54
	s_mov_b32 s16, s56
	s_waitcnt vmcnt(63) expcnt(7) lgkmcnt(15)
	s_barrier
	s_cbranch_vccz .LBB0_725

; __device__ __forceinline__ u16 f2bf(float x) { return (u16)(cvtpk(x, x) & 0xffffu); }
; #define UNR _Pragma("unroll")
; template <int EPI, int lda, int ldb, int N, int K>
; __device__ __forceinline__ void gemm_phase(const u16* __restrict__ A, const u16* __restrict__ Bt, const GemmEpi ep, int wv) {
;     ...
;     if constexpr (EPI == EPI_SWIGLU) {
;       u16* out = reinterpret_cast<u16*>(ep.out0);
;       UNR for (int ai = 0; ai < 2; ++ai) UNR for (int m = 0; m < 4; ++m) {
;         const int rl0 = ai * HALF + wr * 64 + m * 16 + fq * 4;
;         const f32x4 r4 = *reinterpret_cast<const f32x4*>(lrs + rl0);
;         UNR for (int j = 0; j < 4; ++j) {
;           const int row = brow + rl0 + j;
;           const float rs = r4[j], ce = -1.4426950408889634f * rs, r2 = rs * rs;
;           UNR for (int n = 0; n < 2; ++n) {
;             const int col = (bcol >> 1) + wc * 32 + n * 16 + fr;
;             const float g = acc[ai][0][m][n][j], u = acc[ai][1][m][n][j];
;             const float sg = __builtin_amdgcn_rcpf(1.f + __builtin_amdgcn_exp2f(ce * g));
;             out[(size_t)row * ep.ldc + col] = f2bf((g * u) * (r2 * sg));
;           }
;         }
;       }
.LBB0_777:
	s_or_b64 exec, exec, s[56:57]
	v_and_b32_e32 v135, 15, v130
	v_lshrrev_b32_e32 v149, 8, v130
	v_lshl_add_u32 v135, v149, 6, v135
	v_lshlrev_b32_e32 v133, 2, v135
	v_add_u32_e32 v133, 0x20000, v133
	ds_read_b32 v150, v133 offset:0
	ds_read_b32 v151, v133 offset:64
	ds_read_b32 v152, v133 offset:128
	ds_read_b32 v153, v133 offset:192
	v_add_u32_e32 v135, s48, v135
	v_mul_u32_u24_e32 v132, 0x2b00, v135
	v_bfe_u32 v149, v130, 6, 2
	v_lshlrev_b32_e32 v149, 5, v149
	v_bfe_u32 v135, v130, 4, 1
	v_lshl_add_u32 v149, v135, 4, v149
	v_bfe_u32 v135, v130, 5, 1
	v_lshl_add_u32 v149, v135, 3, v149
	v_lshrrev_b32_e64 v135, 1, s49
	v_add_u32_e32 v149, v135, v149
	v_lshl_add_u32 v132, v149, 1, v132
	s_waitcnt lgkmcnt(0)
	v_mul_f32_e32 v135, 0xbfb8aa3b, v150
	v_mul_f32_e32 v149, v150, v150
	ds_read_b32 v150, v133 offset:512
	v_mul_f32_e32 v124, v116, v124
	v_mul_f32_e32 v125, v117, v125
	v_mul_f32_e32 v116, v135, v116
	v_mul_f32_e32 v117, v135, v117
	v_exp_f32_e32 v116, v116
	v_exp_f32_e32 v117, v117
	v_add_f32_e32 v116, 1.0, v116
	v_add_f32_e32 v117, 1.0, v117
	v_rcp_f32_e32 v116, v116
	v_rcp_f32_e32 v117, v117
	v_mul_f32_e32 v116, v149, v116
	v_mul_f32_e32 v117, v149, v117
	v_mul_f32_e32 v124, v124, v116
	v_mul_f32_e32 v125, v125, v117
	v_cvt_pk_bf16_f32 v116, v124, v125
	v_mul_f32_e32 v126, v118, v126
	v_mul_f32_e32 v127, v119, v127
	v_mul_f32_e32 v118, v135, v118
	v_mul_f32_e32 v119, v135, v119
	v_exp_f32_e32 v118, v118
	v_exp_f32_e32 v119, v119
	v_add_f32_e32 v118, 1.0, v118
	v_add_f32_e32 v119, 1.0, v119
	v_rcp_f32_e32 v118, v118
	v_rcp_f32_e32 v119, v119
	v_mul_f32_e32 v118, v149, v118
	v_mul_f32_e32 v119, v149, v119
	v_mul_f32_e32 v126, v126, v118
	v_mul_f32_e32 v127, v127, v119
	v_cvt_pk_bf16_f32 v117, v126, v127
	v_mul_f32_e32 v120, v112, v120
	v_mul_f32_e32 v121, v113, v121
	v_mul_f32_e32 v112, v135, v112
	v_mul_f32_e32 v113, v135, v113
	v_exp_f32_e32 v112, v112
	v_exp_f32_e32 v113, v113
	v_add_f32_e32 v112, 1.0, v112
	v_add_f32_e32 v113, 1.0, v113
	v_rcp_f32_e32 v112, v112
	v_rcp_f32_e32 v113, v113
	v_mul_f32_e32 v112, v149, v112
	v_mul_f32_e32 v113, v149, v113
	v_mul_f32_e32 v120, v120, v112
	v_mul_f32_e32 v121, v121, v113
	v_cvt_pk_bf16_f32 v118, v120, v121
	v_mul_f32_e32 v122, v114, v122
	v_mul_f32_e32 v123, v115, v123
	v_mul_f32_e32 v114, v135, v114
	v_mul_f32_e32 v115, v135, v115
	v_exp_f32_e32 v114, v114
	v_exp_f32_e32 v115, v115
	v_add_f32_e32 v114, 1.0, v114
	v_add_f32_e32 v115, 1.0, v115
	v_rcp_f32_e32 v114, v114
	v_rcp_f32_e32 v115, v115
	v_mul_f32_e32 v114, v149, v114
	v_mul_f32_e32 v115, v149, v115
	v_mul_f32_e32 v122, v122, v114
	v_mul_f32_e32 v123, v123, v115
	v_cvt_pk_bf16_f32 v119, v122, v123
	s_nop 1
	v_permlane16_swap_b32_e32 v116, v118
	v_permlane16_swap_b32_e32 v117, v119
	global_store_dwordx4 v132, v[116:119], s[14:15]
	v_add_u32_e32 v134, 0x2b000, v132
	v_mul_f32_e32 v135, 0xbfb8aa3b, v151
	v_mul_f32_e32 v149, v151, v151
	ds_read_b32 v151, v133 offset:576
	v_mul_f32_e32 v108, v100, v108
	v_mul_f32_e32 v109, v101, v109
	v_mul_f32_e32 v100, v135, v100
	v_mul_f32_e32 v101, v135, v101
	v_exp_f32_e32 v100, v100
	v_exp_f32_e32 v101, v101
	v_add_f32_e32 v100, 1.0, v100
	v_add_f32_e32 v101, 1.0, v101
	v_rcp_f32_e32 v100, v100
	v_rcp_f32_e32 v101, v101
	v_mul_f32_e32 v100, v149, v100
	v_mul_f32_e32 v101, v149, v101
	v_mul_f32_e32 v108, v108, v100
	v_mul_f32_e32 v109, v109, v101
	v_cvt_pk_bf16_f32 v100, v108, v109
	v_mul_f32_e32 v110, v102, v110
	v_mul_f32_e32 v111, v103, v111
	v_mul_f32_e32 v102, v135, v102
	v_mul_f32_e32 v103, v135, v103
	v_exp_f32_e32 v102, v102
	v_exp_f32_e32 v103, v103
	v_add_f32_e32 v102, 1.0, v102
	v_add_f32_e32 v103, 1.0, v103
	v_rcp_f32_e32 v102, v102
	v_rcp_f32_e32 v103, v103
	v_mul_f32_e32 v102, v149, v102
	v_mul_f32_e32 v103, v149, v103
	v_mul_f32_e32 v110, v110, v102
	v_mul_f32_e32 v111, v111, v103
	v_cvt_pk_bf16_f32 v101, v110, v111
	v_mul_f32_e32 v104, v96, v104
	v_mul_f32_e32 v105, v97, v105
	v_mul_f32_e32 v96, v135, v96
	v_mul_f32_e32 v97, v135, v97
	v_exp_f32_e32 v96, v96
	v_exp_f32_e32 v97, v97
	v_add_f32_e32 v96, 1.0, v96
	v_add_f32_e32 v97, 1.0, v97
	v_rcp_f32_e32 v96, v96
	v_rcp_f32_e32 v97, v97
	v_mul_f32_e32 v96, v149, v96
	v_mul_f32_e32 v97, v149, v97
	v_mul_f32_e32 v104, v104, v96
	v_mul_f32_e32 v105, v105, v97
	v_cvt_pk_bf16_f32 v102, v104, v105
	v_mul_f32_e32 v106, v98, v106
	v_mul_f32_e32 v107, v99, v107
	v_mul_f32_e32 v98, v135, v98
	v_mul_f32_e32 v99, v135, v99
	v_exp_f32_e32 v98, v98
	v_exp_f32_e32 v99, v99
	v_add_f32_e32 v98, 1.0, v98
	v_add_f32_e32 v99, 1.0, v99
	v_rcp_f32_e32 v98, v98
	v_rcp_f32_e32 v99, v99
	v_mul_f32_e32 v98, v149, v98
	v_mul_f32_e32 v99, v149, v99
	v_mul_f32_e32 v106, v106, v98
	v_mul_f32_e32 v107, v107, v99
	v_cvt_pk_bf16_f32 v103, v106, v107
	s_nop 1
	v_permlane16_swap_b32_e32 v100, v102
	v_permlane16_swap_b32_e32 v101, v103
	global_store_dwordx4 v134, v[100:103], s[14:15]
	v_add_u32_e32 v134, 0x56000, v132
	v_mul_f32_e32 v135, 0xbfb8aa3b, v152
	v_mul_f32_e32 v149, v152, v152
	ds_read_b32 v152, v133 offset:640
	v_mul_f32_e32 v92, v84, v92
	v_mul_f32_e32 v93, v85, v93
	v_mul_f32_e32 v84, v135, v84
	v_mul_f32_e32 v85, v135, v85
	v_exp_f32_e32 v84, v84
	v_exp_f32_e32 v85, v85
	v_add_f32_e32 v84, 1.0, v84
	v_add_f32_e32 v85, 1.0, v85
	v_rcp_f32_e32 v84, v84
	v_rcp_f32_e32 v85, v85
	v_mul_f32_e32 v84, v149, v84
	v_mul_f32_e32 v85, v149, v85
	v_mul_f32_e32 v92, v92, v84
	v_mul_f32_e32 v93, v93, v85
	v_cvt_pk_bf16_f32 v84, v92, v93
	v_mul_f32_e32 v94, v86, v94
	v_mul_f32_e32 v95, v87, v95
	v_mul_f32_e32 v86, v135, v86
	v_mul_f32_e32 v87, v135, v87
	v_exp_f32_e32 v86, v86
	v_exp_f32_e32 v87, v87
	v_add_f32_e32 v86, 1.0, v86
	v_add_f32_e32 v87, 1.0, v87
; __device__ __forceinline__ u16 f2bf(float x) { return (u16)(cvtpk(x, x) & 0xffffu); }
; #define UNR _Pragma("unroll")
; template <int EPI, int lda, int ldb, int N, int K>
; __device__ __forceinline__ void gemm_phase(const u16* __restrict__ A, const u16* __restrict__ Bt, const GemmEpi ep, int wv) {
;     ...
;     if constexpr (EPI == EPI_SWIGLU) {
;       u16* out = reinterpret_cast<u16*>(ep.out0);
;       UNR for (int ai = 0; ai < 2; ++ai) UNR for (int m = 0; m < 4; ++m) {
;         const int rl0 = ai * HALF + wr * 64 + m * 16 + fq * 4;
;         const f32x4 r4 = *reinterpret_cast<const f32x4*>(lrs + rl0);
;         UNR for (int j = 0; j < 4; ++j) {
;           const int row = brow + rl0 + j;
;           const float rs = r4[j], ce = -1.4426950408889634f * rs, r2 = rs * rs;
;           UNR for (int n = 0; n < 2; ++n) {
;             const int col = (bcol >> 1) + wc * 32 + n * 16 + fr;
;             const float g = acc[ai][0][m][n][j], u = acc[ai][1][m][n][j];
;             const float sg = __builtin_amdgcn_rcpf(1.f + __builtin_amdgcn_exp2f(ce * g));
;             out[(size_t)row * ep.ldc + col] = f2bf((g * u) * (r2 * sg));
;           }
;         }
;       }
	v_rcp_f32_e32 v86, v86
	v_rcp_f32_e32 v87, v87
	v_mul_f32_e32 v86, v149, v86
	v_mul_f32_e32 v87, v149, v87
	v_mul_f32_e32 v94, v94, v86
	v_mul_f32_e32 v95, v95, v87
	v_cvt_pk_bf16_f32 v85, v94, v95
	v_mul_f32_e32 v88, v80, v88
	v_mul_f32_e32 v89, v81, v89
	v_mul_f32_e32 v80, v135, v80
	v_mul_f32_e32 v81, v135, v81
	v_exp_f32_e32 v80, v80
	v_exp_f32_e32 v81, v81
	v_add_f32_e32 v80, 1.0, v80
	v_add_f32_e32 v81, 1.0, v81
	v_rcp_f32_e32 v80, v80
	v_rcp_f32_e32 v81, v81
	v_mul_f32_e32 v80, v149, v80
	v_mul_f32_e32 v81, v149, v81
	v_mul_f32_e32 v88, v88, v80
	v_mul_f32_e32 v89, v89, v81
	v_cvt_pk_bf16_f32 v86, v88, v89
	v_mul_f32_e32 v90, v82, v90
	v_mul_f32_e32 v91, v83, v91
	v_mul_f32_e32 v82, v135, v82
	v_mul_f32_e32 v83, v135, v83
	v_exp_f32_e32 v82, v82
	v_exp_f32_e32 v83, v83
	v_add_f32_e32 v82, 1.0, v82
	v_add_f32_e32 v83, 1.0, v83
	v_rcp_f32_e32 v82, v82
	v_rcp_f32_e32 v83, v83
	v_mul_f32_e32 v82, v149, v82
	v_mul_f32_e32 v83, v149, v83
	v_mul_f32_e32 v90, v90, v82
	v_mul_f32_e32 v91, v91, v83
	v_cvt_pk_bf16_f32 v87, v90, v91
	s_nop 1
	v_permlane16_swap_b32_e32 v84, v86
	v_permlane16_swap_b32_e32 v85, v87
	global_store_dwordx4 v134, v[84:87], s[14:15]
	v_add_u32_e32 v134, 0x81000, v132
	v_mul_f32_e32 v135, 0xbfb8aa3b, v153
	v_mul_f32_e32 v149, v153, v153
	ds_read_b32 v153, v133 offset:704
	v_mul_f32_e32 v76, v68, v76
	v_mul_f32_e32 v77, v69, v77
	v_mul_f32_e32 v68, v135, v68
	v_mul_f32_e32 v69, v135, v69
	v_exp_f32_e32 v68, v68
	v_exp_f32_e32 v69, v69
	v_add_f32_e32 v68, 1.0, v68
	v_add_f32_e32 v69, 1.0, v69
	v_rcp_f32_e32 v68, v68
	v_rcp_f32_e32 v69, v69
	v_mul_f32_e32 v68, v149, v68
	v_mul_f32_e32 v69, v149, v69
	v_mul_f32_e32 v76, v76, v68
	v_mul_f32_e32 v77, v77, v69
	v_cvt_pk_bf16_f32 v68, v76, v77
	v_mul_f32_e32 v78, v70, v78
	v_mul_f32_e32 v79, v71, v79
	v_mul_f32_e32 v70, v135, v70
	v_mul_f32_e32 v71, v135, v71
	v_exp_f32_e32 v70, v70
	v_exp_f32_e32 v71, v71
	v_add_f32_e32 v70, 1.0, v70
	v_add_f32_e32 v71, 1.0, v71
	v_rcp_f32_e32 v70, v70
	v_rcp_f32_e32 v71, v71
	v_mul_f32_e32 v70, v149, v70
	v_mul_f32_e32 v71, v149, v71
	v_mul_f32_e32 v78, v78, v70
	v_mul_f32_e32 v79, v79, v71
	v_cvt_pk_bf16_f32 v69, v78, v79
	v_mul_f32_e32 v72, v64, v72
	v_mul_f32_e32 v73, v65, v73
	v_mul_f32_e32 v64, v135, v64
	v_mul_f32_e32 v65, v135, v65
	v_exp_f32_e32 v64, v64
	v_exp_f32_e32 v65, v65
	v_add_f32_e32 v64, 1.0, v64
	v_add_f32_e32 v65, 1.0, v65
	v_rcp_f32_e32 v64, v64
	v_rcp_f32_e32 v65, v65
	v_mul_f32_e32 v64, v149, v64
	v_mul_f32_e32 v65, v149, v65
	v_mul_f32_e32 v72, v72, v64
	v_mul_f32_e32 v73, v73, v65
	v_cvt_pk_bf16_f32 v70, v72, v73
	v_mul_f32_e32 v74, v66, v74
	v_mul_f32_e32 v75, v67, v75
	v_mul_f32_e32 v66, v135, v66
	v_mul_f32_e32 v67, v135, v67
	v_exp_f32_e32 v66, v66
	v_exp_f32_e32 v67, v67
	v_add_f32_e32 v66, 1.0, v66
	v_add_f32_e32 v67, 1.0, v67
	v_rcp_f32_e32 v66, v66
	v_rcp_f32_e32 v67, v67
	v_mul_f32_e32 v66, v149, v66
	v_mul_f32_e32 v67, v149, v67
	v_mul_f32_e32 v74, v74, v66
	v_mul_f32_e32 v75, v75, v67
	v_cvt_pk_bf16_f32 v71, v74, v75
	s_nop 1
	v_permlane16_swap_b32_e32 v68, v70
	v_permlane16_swap_b32_e32 v69, v71
	global_store_dwordx4 v134, v[68:71], s[14:15]
	s_waitcnt lgkmcnt(0)
	v_add_u32_e32 v134, 0x158000, v132
	v_mul_f32_e32 v135, 0xbfb8aa3b, v150
	v_mul_f32_e32 v149, v150, v150
	v_mul_f32_e32 v60, v52, v60
	v_mul_f32_e32 v61, v53, v61
	v_mul_f32_e32 v52, v135, v52
	v_mul_f32_e32 v53, v135, v53
	v_exp_f32_e32 v52, v52
	v_exp_f32_e32 v53, v53
	v_add_f32_e32 v52, 1.0, v52
	v_add_f32_e32 v53, 1.0, v53
	v_rcp_f32_e32 v52, v52
	v_rcp_f32_e32 v53, v53
	v_mul_f32_e32 v52, v149, v52
	v_mul_f32_e32 v53, v149, v53
	v_mul_f32_e32 v60, v60, v52
	v_mul_f32_e32 v61, v61, v53
	v_cvt_pk_bf16_f32 v52, v60, v61
	v_mul_f32_e32 v62, v54, v62
	v_mul_f32_e32 v63, v55, v63
	v_mul_f32_e32 v54, v135, v54
	v_mul_f32_e32 v55, v135, v55
	v_exp_f32_e32 v54, v54
	v_exp_f32_e32 v55, v55
	v_add_f32_e32 v54, 1.0, v54
	v_add_f32_e32 v55, 1.0, v55
	v_rcp_f32_e32 v54, v54
	v_rcp_f32_e32 v55, v55
	v_mul_f32_e32 v54, v149, v54
	v_mul_f32_e32 v55, v149, v55
	v_mul_f32_e32 v62, v62, v54
	v_mul_f32_e32 v63, v63, v55
	v_cvt_pk_bf16_f32 v53, v62, v63
	v_mul_f32_e32 v56, v48, v56
	v_mul_f32_e32 v57, v49, v57
	v_mul_f32_e32 v48, v135, v48
	v_mul_f32_e32 v49, v135, v49
	v_exp_f32_e32 v48, v48
	v_exp_f32_e32 v49, v49
	v_add_f32_e32 v48, 1.0, v48
	v_add_f32_e32 v49, 1.0, v49
	v_rcp_f32_e32 v48, v48
	v_rcp_f32_e32 v49, v49
	v_mul_f32_e32 v48, v149, v48
	v_mul_f32_e32 v49, v149, v49
	v_mul_f32_e32 v56, v56, v48
	v_mul_f32_e32 v57, v57, v49
	v_cvt_pk_bf16_f32 v54, v56, v57
	v_mul_f32_e32 v58, v50, v58
	v_mul_f32_e32 v59, v51, v59
	v_mul_f32_e32 v50, v135, v50
	v_mul_f32_e32 v51, v135, v51
	v_exp_f32_e32 v50, v50
	v_exp_f32_e32 v51, v51
	v_add_f32_e32 v50, 1.0, v50
	v_add_f32_e32 v51, 1.0, v51
	v_rcp_f32_e32 v50, v50
	v_rcp_f32_e32 v51, v51
	v_mul_f32_e32 v50, v149, v50
	v_mul_f32_e32 v51, v149, v51
	v_mul_f32_e32 v58, v58, v50
	v_mul_f32_e32 v59, v59, v51
	v_cvt_pk_bf16_f32 v55, v58, v59
	s_nop 1
	v_permlane16_swap_b32_e32 v52, v54
	v_permlane16_swap_b32_e32 v53, v55
	global_store_dwordx4 v134, v[52:55], s[14:15]
	v_add_u32_e32 v134, 0x183000, v132
	v_mul_f32_e32 v135, 0xbfb8aa3b, v151
	v_mul_f32_e32 v149, v151, v151
	v_mul_f32_e32 v44, v36, v44
	v_mul_f32_e32 v45, v37, v45
	v_mul_f32_e32 v36, v135, v36
	v_mul_f32_e32 v37, v135, v37
	v_exp_f32_e32 v36, v36
	v_exp_f32_e32 v37, v37
	v_add_f32_e32 v36, 1.0, v36
	v_add_f32_e32 v37, 1.0, v37
	v_rcp_f32_e32 v36, v36
	v_rcp_f32_e32 v37, v37
	v_mul_f32_e32 v36, v149, v36
	v_mul_f32_e32 v37, v149, v37
	v_mul_f32_e32 v44, v44, v36
	v_mul_f32_e32 v45, v45, v37
	v_cvt_pk_bf16_f32 v36, v44, v45
	v_mul_f32_e32 v46, v38, v46
; __device__ __forceinline__ u16 f2bf(float x) { return (u16)(cvtpk(x, x) & 0xffffu); }
; #define UNR _Pragma("unroll")
; #define WAIT_V(n) asm volatile("s_waitcnt vmcnt(" #n ")" ::: "memory")
; template <int EPI, int lda, int ldb, int N, int K>
; __device__ __forceinline__ void gemm_phase(const u16* __restrict__ A, const u16* __restrict__ Bt, const GemmEpi ep, int wv) {
;     ...
;     if constexpr (EPI == EPI_SWIGLU) {
;       u16* out = reinterpret_cast<u16*>(ep.out0);
;       UNR for (int ai = 0; ai < 2; ++ai) UNR for (int m = 0; m < 4; ++m) {
;         const int rl0 = ai * HALF + wr * 64 + m * 16 + fq * 4;
;         const f32x4 r4 = *reinterpret_cast<const f32x4*>(lrs + rl0);
;         UNR for (int j = 0; j < 4; ++j) {
;           const int row = brow + rl0 + j;
;           const float rs = r4[j], ce = -1.4426950408889634f * rs, r2 = rs * rs;
;           UNR for (int n = 0; n < 2; ++n) {
;             const int col = (bcol >> 1) + wc * 32 + n * 16 + fr;
;             const float g = acc[ai][0][m][n][j], u = acc[ai][1][m][n][j];
;             const float sg = __builtin_amdgcn_rcpf(1.f + __builtin_amdgcn_exp2f(ce * g));
;             out[(size_t)row * ep.ldc + col] = f2bf((g * u) * (r2 * sg));
;           }
;         }
;       }
;     ...
;     if constexpr (PF) {
;       WAIT_V(0);
;       __syncthreads();
;       if constexpr (CONS) { if (more && tidx < 256) { float sq = 0.f; UNR for (int pp = 0; pp < 8; ++pp) sq += nss[pp];
;         lrs[tidx] = rsqrtf(sq * (1.f / DM) + 1e-6f); } }
;       if (!more) break;
	v_mul_f32_e32 v47, v39, v47
	v_mul_f32_e32 v38, v135, v38
	v_mul_f32_e32 v39, v135, v39
	v_exp_f32_e32 v38, v38
	v_exp_f32_e32 v39, v39
	v_add_f32_e32 v38, 1.0, v38
	v_add_f32_e32 v39, 1.0, v39
	v_rcp_f32_e32 v38, v38
	v_rcp_f32_e32 v39, v39
	v_mul_f32_e32 v38, v149, v38
	v_mul_f32_e32 v39, v149, v39
	v_mul_f32_e32 v46, v46, v38
	v_mul_f32_e32 v47, v47, v39
	v_cvt_pk_bf16_f32 v37, v46, v47
	v_mul_f32_e32 v40, v32, v40
	v_mul_f32_e32 v41, v33, v41
	v_mul_f32_e32 v32, v135, v32
	v_mul_f32_e32 v33, v135, v33
	v_exp_f32_e32 v32, v32
	v_exp_f32_e32 v33, v33
	v_add_f32_e32 v32, 1.0, v32
	v_add_f32_e32 v33, 1.0, v33
	v_rcp_f32_e32 v32, v32
	v_rcp_f32_e32 v33, v33
	v_mul_f32_e32 v32, v149, v32
	v_mul_f32_e32 v33, v149, v33
	v_mul_f32_e32 v40, v40, v32
	v_mul_f32_e32 v41, v41, v33
	v_cvt_pk_bf16_f32 v38, v40, v41
	v_mul_f32_e32 v42, v34, v42
	v_mul_f32_e32 v43, v35, v43
	v_mul_f32_e32 v34, v135, v34
	v_mul_f32_e32 v35, v135, v35
	v_exp_f32_e32 v34, v34
	v_exp_f32_e32 v35, v35
	v_add_f32_e32 v34, 1.0, v34
	v_add_f32_e32 v35, 1.0, v35
	v_rcp_f32_e32 v34, v34
	v_rcp_f32_e32 v35, v35
	v_mul_f32_e32 v34, v149, v34
	v_mul_f32_e32 v35, v149, v35
	v_mul_f32_e32 v42, v42, v34
	v_mul_f32_e32 v43, v43, v35
	v_cvt_pk_bf16_f32 v39, v42, v43
	s_nop 1
	v_permlane16_swap_b32_e32 v36, v38
	v_permlane16_swap_b32_e32 v37, v39
	global_store_dwordx4 v134, v[36:39], s[14:15]
	v_add_u32_e32 v134, 0x1ae000, v132
	v_mul_f32_e32 v135, 0xbfb8aa3b, v152
	v_mul_f32_e32 v149, v152, v152
	v_mul_f32_e32 v28, v20, v28
	v_mul_f32_e32 v29, v21, v29
	v_mul_f32_e32 v20, v135, v20
	v_mul_f32_e32 v21, v135, v21
	v_exp_f32_e32 v20, v20
	v_exp_f32_e32 v21, v21
	v_add_f32_e32 v20, 1.0, v20
	v_add_f32_e32 v21, 1.0, v21
	v_rcp_f32_e32 v20, v20
	v_rcp_f32_e32 v21, v21
	v_mul_f32_e32 v20, v149, v20
	v_mul_f32_e32 v21, v149, v21
	v_mul_f32_e32 v28, v28, v20
	v_mul_f32_e32 v29, v29, v21
	v_cvt_pk_bf16_f32 v20, v28, v29
	v_mul_f32_e32 v30, v22, v30
	v_mul_f32_e32 v31, v23, v31
	v_mul_f32_e32 v22, v135, v22
	v_mul_f32_e32 v23, v135, v23
	v_exp_f32_e32 v22, v22
	v_exp_f32_e32 v23, v23
	v_add_f32_e32 v22, 1.0, v22
	v_add_f32_e32 v23, 1.0, v23
	v_rcp_f32_e32 v22, v22
	v_rcp_f32_e32 v23, v23
	v_mul_f32_e32 v22, v149, v22
	v_mul_f32_e32 v23, v149, v23
	v_mul_f32_e32 v30, v30, v22
	v_mul_f32_e32 v31, v31, v23
	v_cvt_pk_bf16_f32 v21, v30, v31
	v_mul_f32_e32 v24, v16, v24
	v_mul_f32_e32 v25, v17, v25
	v_mul_f32_e32 v16, v135, v16
	v_mul_f32_e32 v17, v135, v17
	v_exp_f32_e32 v16, v16
	v_exp_f32_e32 v17, v17
	v_add_f32_e32 v16, 1.0, v16
	v_add_f32_e32 v17, 1.0, v17
	v_rcp_f32_e32 v16, v16
	v_rcp_f32_e32 v17, v17
	v_mul_f32_e32 v16, v149, v16
	v_mul_f32_e32 v17, v149, v17
	v_mul_f32_e32 v24, v24, v16
	v_mul_f32_e32 v25, v25, v17
	v_cvt_pk_bf16_f32 v22, v24, v25
	v_mul_f32_e32 v26, v18, v26
	v_mul_f32_e32 v27, v19, v27
	v_mul_f32_e32 v18, v135, v18
	v_mul_f32_e32 v19, v135, v19
	v_exp_f32_e32 v18, v18
	v_exp_f32_e32 v19, v19
	v_add_f32_e32 v18, 1.0, v18
	v_add_f32_e32 v19, 1.0, v19
	v_rcp_f32_e32 v18, v18
	v_rcp_f32_e32 v19, v19
	v_mul_f32_e32 v18, v149, v18
	v_mul_f32_e32 v19, v149, v19
	v_mul_f32_e32 v26, v26, v18
	v_mul_f32_e32 v27, v27, v19
	v_cvt_pk_bf16_f32 v23, v26, v27
	s_nop 1
	v_permlane16_swap_b32_e32 v20, v22
	v_permlane16_swap_b32_e32 v21, v23
	global_store_dwordx4 v134, v[20:23], s[14:15]
	v_add_u32_e32 v134, 0x1d9000, v132
	v_mul_f32_e32 v135, 0xbfb8aa3b, v153
	v_mul_f32_e32 v149, v153, v153
	v_mul_f32_e32 v12, v4, v12
	v_mul_f32_e32 v13, v5, v13
	v_mul_f32_e32 v4, v135, v4
	v_mul_f32_e32 v5, v135, v5
	v_exp_f32_e32 v4, v4
	v_exp_f32_e32 v5, v5
	v_add_f32_e32 v4, 1.0, v4
	v_add_f32_e32 v5, 1.0, v5
	v_rcp_f32_e32 v4, v4
	v_rcp_f32_e32 v5, v5
	v_mul_f32_e32 v4, v149, v4
	v_mul_f32_e32 v5, v149, v5
	v_mul_f32_e32 v12, v12, v4
	v_mul_f32_e32 v13, v13, v5
	v_cvt_pk_bf16_f32 v4, v12, v13
	v_mul_f32_e32 v14, v6, v14
	v_mul_f32_e32 v15, v7, v15
	v_mul_f32_e32 v6, v135, v6
	v_mul_f32_e32 v7, v135, v7
	v_exp_f32_e32 v6, v6
	v_exp_f32_e32 v7, v7
	v_add_f32_e32 v6, 1.0, v6
	v_add_f32_e32 v7, 1.0, v7
	v_rcp_f32_e32 v6, v6
	v_rcp_f32_e32 v7, v7
	v_mul_f32_e32 v6, v149, v6
	v_mul_f32_e32 v7, v149, v7
	v_mul_f32_e32 v14, v14, v6
	v_mul_f32_e32 v15, v15, v7
	v_cvt_pk_bf16_f32 v5, v14, v15
	v_mul_f32_e32 v8, v0, v8
	v_mul_f32_e32 v9, v1, v9
	v_mul_f32_e32 v0, v135, v0
	v_mul_f32_e32 v1, v135, v1
	v_exp_f32_e32 v0, v0
	v_exp_f32_e32 v1, v1
	v_add_f32_e32 v0, 1.0, v0
	v_add_f32_e32 v1, 1.0, v1
	v_rcp_f32_e32 v0, v0
	v_rcp_f32_e32 v1, v1
	v_mul_f32_e32 v0, v149, v0
	v_mul_f32_e32 v1, v149, v1
	v_mul_f32_e32 v8, v8, v0
	v_mul_f32_e32 v9, v9, v1
	v_cvt_pk_bf16_f32 v6, v8, v9
	v_mul_f32_e32 v10, v2, v10
	v_mul_f32_e32 v11, v3, v11
	v_mul_f32_e32 v2, v135, v2
	v_mul_f32_e32 v3, v135, v3
	v_exp_f32_e32 v2, v2
	v_exp_f32_e32 v3, v3
	v_add_f32_e32 v2, 1.0, v2
	v_add_f32_e32 v3, 1.0, v3
	v_rcp_f32_e32 v2, v2
	v_rcp_f32_e32 v3, v3
	v_mul_f32_e32 v2, v149, v2
	v_mul_f32_e32 v3, v149, v3
	v_mul_f32_e32 v10, v10, v2
	v_mul_f32_e32 v11, v11, v3
	v_cvt_pk_bf16_f32 v7, v10, v11
	s_nop 1
	v_permlane16_swap_b32_e32 v4, v6
	v_permlane16_swap_b32_e32 v5, v7
	global_store_dwordx4 v134, v[4:7], s[14:15]
	s_waitcnt vmcnt(8)
	s_waitcnt vmcnt(8)
	v_add_f32_e32 v148, 0, v131
	s_barrier
	s_and_saveexec_b64 s[48:49], s[54:55]
	s_cbranch_execz .LBB0_766
	v_add_f32_e32 v0, v141, v148
	v_add_f32_e32 v0, v140, v0
	v_add_f32_e32 v0, v139, v0
	v_add_f32_e32 v0, v138, v0
	v_add_f32_e32 v0, v137, v0
	v_add_f32_e32 v0, v136, v0
	v_add_f32_e32 v0, v128, v0
	v_fmamk_f32 v0, v0, 0x3a000000, v143
	v_mul_f32_e32 v1, 0x4b800000, v0
	v_cmp_gt_f32_e32 vcc, s73, v0
	s_nop 1
	v_cndmask_b32_e32 v0, v0, v1, vcc
	v_rsq_f32_e32 v0, v0
	v_lshl_add_u32 v1, v130, 2, 0
	v_add_u32_e32 v1, 0x20000, v1
	v_mul_f32_e32 v2, 0x45800000, v0
	v_cndmask_b32_e32 v0, v0, v2, vcc
	ds_write_b32 v1, v0
	s_branch .LBB0_766

; #define UNR _Pragma("unroll")
; #define WAIT_V(n) asm volatile("s_waitcnt vmcnt(" #n ")" ::: "memory")
; template <int EPI, int lda, int ldb, int N, int K>
; __device__ __forceinline__ void gemm_phase(const u16* __restrict__ A, const u16* __restrict__ Bt, const GemmEpi ep, int wv) {
;     ...
;     if constexpr (PF) {
;       WAIT_V(0);
;       __syncthreads();
;       if constexpr (CONS) { if (more && tidx < 256) { float sq = 0.f; UNR for (int pp = 0; pp < 8; ++pp) sq += nss[pp];
;         lrs[tidx] = rsqrtf(sq * (1.f / DM) + 1e-6f); } }
;       if (!more) break;
;       tile = ntile; brow = nbrow; bcol = nbcol; pn = npn;
.LBB0_834:
	s_or_b64 exec, exec, s[52:53]
	s_waitcnt vmcnt(17)
	s_andn2_b64 vcc, exec, s[50:51]
	s_mov_b32 s61, s73
	s_mov_b32 s52, s74
	s_mov_b32 s18, s72
	s_waitcnt vmcnt(63) expcnt(7) lgkmcnt(15)
	s_barrier
	s_cbranch_vccz .LBB0_909

; #define UNR _Pragma("unroll")
; #define WAIT_V(n) asm volatile("s_waitcnt vmcnt(" #n ")" ::: "memory")
; template <int EPI, int lda, int ldb, int N, int K>
; __device__ __forceinline__ void gemm_phase(const u16* __restrict__ A, const u16* __restrict__ Bt, const GemmEpi ep, int wv) {
;     ...
;     if constexpr (PF) {
;       WAIT_V(0);
;       __syncthreads();
;       if constexpr (CONS) { if (more && tidx < 256) { float sq = 0.f; UNR for (int pp = 0; pp < 8; ++pp) sq += nss[pp];
;         lrs[tidx] = rsqrtf(sq * (1.f / DM) + 1e-6f); } }
;       if (!more) break;
;       tile = ntile; brow = nbrow; bcol = nbcol; pn = npn;
.LBB0_1444:
	s_or_b64 exec, exec, s[50:51]
	s_waitcnt vmcnt(17)
	s_andn2_b64 vcc, exec, s[44:45]
	s_mov_b32 s54, s63
	s_mov_b32 s50, s46
	s_mov_b32 s16, s48
	s_waitcnt vmcnt(63) expcnt(7) lgkmcnt(15)
	s_barrier
	s_cbranch_vccz .LBB0_1519

; __device__ __forceinline__ u16 f2bf(float x) { return (u16)(cvtpk(x, x) & 0xffffu); }
; #define UNR _Pragma("unroll")
; template <int EPI, int lda, int ldb, int N, int K>
; __device__ __forceinline__ void gemm_phase(const u16* __restrict__ A, const u16* __restrict__ Bt, const GemmEpi ep, int wv) {
;     ...
;     if constexpr (EPI == EPI_SWIGLU) {
;       u16* out = reinterpret_cast<u16*>(ep.out0);
;       UNR for (int ai = 0; ai < 2; ++ai) UNR for (int m = 0; m < 4; ++m) {
;         const int rl0 = ai * HALF + wr * 64 + m * 16 + fq * 4;
;         const f32x4 r4 = *reinterpret_cast<const f32x4*>(lrs + rl0);
;         UNR for (int j = 0; j < 4; ++j) {
;           const int row = brow + rl0 + j;
;           const float rs = r4[j], ce = -1.4426950408889634f * rs, r2 = rs * rs;
;           UNR for (int n = 0; n < 2; ++n) {
;             const int col = (bcol >> 1) + wc * 32 + n * 16 + fr;
;             const float g = acc[ai][0][m][n][j], u = acc[ai][1][m][n][j];
;             const float sg = __builtin_amdgcn_rcpf(1.f + __builtin_amdgcn_exp2f(ce * g));
;             out[(size_t)row * ep.ldc + col] = f2bf((g * u) * (r2 * sg));
;           }
;         }
;       }
.LBB0_1571:
	s_or_b64 exec, exec, s[46:47]
	v_and_b32_e32 v135, 15, v130
	v_lshrrev_b32_e32 v149, 8, v130
	v_lshl_add_u32 v135, v149, 6, v135
	v_lshlrev_b32_e32 v133, 2, v135
	v_add_u32_e32 v133, 0x20000, v133
	ds_read_b32 v150, v133 offset:0
	ds_read_b32 v151, v133 offset:64
	ds_read_b32 v152, v133 offset:128
	ds_read_b32 v153, v133 offset:192
	v_add_u32_e32 v135, s38, v135
	v_mul_u32_u24_e32 v132, 0x2b00, v135
	v_bfe_u32 v149, v130, 6, 2
	v_lshlrev_b32_e32 v149, 5, v149
	v_bfe_u32 v135, v130, 4, 1
	v_lshl_add_u32 v149, v135, 4, v149
	v_bfe_u32 v135, v130, 5, 1
	v_lshl_add_u32 v149, v135, 3, v149
	v_lshrrev_b32_e64 v135, 1, s39
	v_add_u32_e32 v149, v135, v149
	v_lshl_add_u32 v132, v149, 1, v132
	s_waitcnt lgkmcnt(0)
	v_mul_f32_e32 v135, 0xbfb8aa3b, v150
	v_mul_f32_e32 v149, v150, v150
	ds_read_b32 v150, v133 offset:512
	v_mul_f32_e32 v124, v116, v124
	v_mul_f32_e32 v125, v117, v125
	v_mul_f32_e32 v116, v135, v116
	v_mul_f32_e32 v117, v135, v117
	v_exp_f32_e32 v116, v116
	v_exp_f32_e32 v117, v117
	v_add_f32_e32 v116, 1.0, v116
	v_add_f32_e32 v117, 1.0, v117
	v_rcp_f32_e32 v116, v116
	v_rcp_f32_e32 v117, v117
	v_mul_f32_e32 v116, v149, v116
	v_mul_f32_e32 v117, v149, v117
	v_mul_f32_e32 v124, v124, v116
	v_mul_f32_e32 v125, v125, v117
	v_cvt_pk_bf16_f32 v116, v124, v125
	v_mul_f32_e32 v126, v118, v126
	v_mul_f32_e32 v127, v119, v127
	v_mul_f32_e32 v118, v135, v118
	v_mul_f32_e32 v119, v135, v119
	v_exp_f32_e32 v118, v118
	v_exp_f32_e32 v119, v119
	v_add_f32_e32 v118, 1.0, v118
	v_add_f32_e32 v119, 1.0, v119
	v_rcp_f32_e32 v118, v118
	v_rcp_f32_e32 v119, v119
	v_mul_f32_e32 v118, v149, v118
	v_mul_f32_e32 v119, v149, v119
	v_mul_f32_e32 v126, v126, v118
	v_mul_f32_e32 v127, v127, v119
	v_cvt_pk_bf16_f32 v117, v126, v127
	v_mul_f32_e32 v120, v112, v120
	v_mul_f32_e32 v121, v113, v121
	v_mul_f32_e32 v112, v135, v112
	v_mul_f32_e32 v113, v135, v113
	v_exp_f32_e32 v112, v112
	v_exp_f32_e32 v113, v113
	v_add_f32_e32 v112, 1.0, v112
	v_add_f32_e32 v113, 1.0, v113
	v_rcp_f32_e32 v112, v112
	v_rcp_f32_e32 v113, v113
	v_mul_f32_e32 v112, v149, v112
	v_mul_f32_e32 v113, v149, v113
	v_mul_f32_e32 v120, v120, v112
	v_mul_f32_e32 v121, v121, v113
	v_cvt_pk_bf16_f32 v118, v120, v121
	v_mul_f32_e32 v122, v114, v122
	v_mul_f32_e32 v123, v115, v123
	v_mul_f32_e32 v114, v135, v114
	v_mul_f32_e32 v115, v135, v115
	v_exp_f32_e32 v114, v114
	v_exp_f32_e32 v115, v115
	v_add_f32_e32 v114, 1.0, v114
	v_add_f32_e32 v115, 1.0, v115
	v_rcp_f32_e32 v114, v114
	v_rcp_f32_e32 v115, v115
	v_mul_f32_e32 v114, v149, v114
	v_mul_f32_e32 v115, v149, v115
	v_mul_f32_e32 v122, v122, v114
	v_mul_f32_e32 v123, v123, v115
	v_cvt_pk_bf16_f32 v119, v122, v123
	s_nop 1
	v_permlane16_swap_b32_e32 v116, v118
	v_permlane16_swap_b32_e32 v117, v119
	global_store_dwordx4 v132, v[116:119], s[10:11]
	v_add_u32_e32 v134, 0x2b000, v132
	v_mul_f32_e32 v135, 0xbfb8aa3b, v151
	v_mul_f32_e32 v149, v151, v151
	ds_read_b32 v151, v133 offset:576
	v_mul_f32_e32 v108, v100, v108
	v_mul_f32_e32 v109, v101, v109
	v_mul_f32_e32 v100, v135, v100
	v_mul_f32_e32 v101, v135, v101
	v_exp_f32_e32 v100, v100
	v_exp_f32_e32 v101, v101
	v_add_f32_e32 v100, 1.0, v100
	v_add_f32_e32 v101, 1.0, v101
	v_rcp_f32_e32 v100, v100
	v_rcp_f32_e32 v101, v101
	v_mul_f32_e32 v100, v149, v100
	v_mul_f32_e32 v101, v149, v101
	v_mul_f32_e32 v108, v108, v100
	v_mul_f32_e32 v109, v109, v101
	v_cvt_pk_bf16_f32 v100, v108, v109
	v_mul_f32_e32 v110, v102, v110
	v_mul_f32_e32 v111, v103, v111
	v_mul_f32_e32 v102, v135, v102
	v_mul_f32_e32 v103, v135, v103
	v_exp_f32_e32 v102, v102
	v_exp_f32_e32 v103, v103
	v_add_f32_e32 v102, 1.0, v102
	v_add_f32_e32 v103, 1.0, v103
	v_rcp_f32_e32 v102, v102
	v_rcp_f32_e32 v103, v103
	v_mul_f32_e32 v102, v149, v102
	v_mul_f32_e32 v103, v149, v103
	v_mul_f32_e32 v110, v110, v102
	v_mul_f32_e32 v111, v111, v103
	v_cvt_pk_bf16_f32 v101, v110, v111
	v_mul_f32_e32 v104, v96, v104
	v_mul_f32_e32 v105, v97, v105
	v_mul_f32_e32 v96, v135, v96
	v_mul_f32_e32 v97, v135, v97
	v_exp_f32_e32 v96, v96
	v_exp_f32_e32 v97, v97
	v_add_f32_e32 v96, 1.0, v96
	v_add_f32_e32 v97, 1.0, v97
	v_rcp_f32_e32 v96, v96
	v_rcp_f32_e32 v97, v97
	v_mul_f32_e32 v96, v149, v96
	v_mul_f32_e32 v97, v149, v97
	v_mul_f32_e32 v104, v104, v96
	v_mul_f32_e32 v105, v105, v97
	v_cvt_pk_bf16_f32 v102, v104, v105
	v_mul_f32_e32 v106, v98, v106
	v_mul_f32_e32 v107, v99, v107
	v_mul_f32_e32 v98, v135, v98
	v_mul_f32_e32 v99, v135, v99
	v_exp_f32_e32 v98, v98
	v_exp_f32_e32 v99, v99
	v_add_f32_e32 v98, 1.0, v98
	v_add_f32_e32 v99, 1.0, v99
	v_rcp_f32_e32 v98, v98
	v_rcp_f32_e32 v99, v99
	v_mul_f32_e32 v98, v149, v98
	v_mul_f32_e32 v99, v149, v99
	v_mul_f32_e32 v106, v106, v98
	v_mul_f32_e32 v107, v107, v99
	v_cvt_pk_bf16_f32 v103, v106, v107
	s_nop 1
	v_permlane16_swap_b32_e32 v100, v102
	v_permlane16_swap_b32_e32 v101, v103
	global_store_dwordx4 v134, v[100:103], s[10:11]
	v_add_u32_e32 v134, 0x56000, v132
	v_mul_f32_e32 v135, 0xbfb8aa3b, v152
	v_mul_f32_e32 v149, v152, v152
	ds_read_b32 v152, v133 offset:640
	v_mul_f32_e32 v92, v84, v92
	v_mul_f32_e32 v93, v85, v93
	v_mul_f32_e32 v84, v135, v84
	v_mul_f32_e32 v85, v135, v85
	v_exp_f32_e32 v84, v84
	v_exp_f32_e32 v85, v85
	v_add_f32_e32 v84, 1.0, v84
	v_add_f32_e32 v85, 1.0, v85
	v_rcp_f32_e32 v84, v84
	v_rcp_f32_e32 v85, v85
	v_mul_f32_e32 v84, v149, v84
	v_mul_f32_e32 v85, v149, v85
	v_mul_f32_e32 v92, v92, v84
	v_mul_f32_e32 v93, v93, v85
	v_cvt_pk_bf16_f32 v84, v92, v93
	v_mul_f32_e32 v94, v86, v94
	v_mul_f32_e32 v95, v87, v95
	v_mul_f32_e32 v86, v135, v86
	v_mul_f32_e32 v87, v135, v87
	v_exp_f32_e32 v86, v86
	v_exp_f32_e32 v87, v87
	v_add_f32_e32 v86, 1.0, v86
	v_add_f32_e32 v87, 1.0, v87
; __device__ __forceinline__ u16 f2bf(float x) { return (u16)(cvtpk(x, x) & 0xffffu); }
; #define UNR _Pragma("unroll")
; template <int EPI, int lda, int ldb, int N, int K>
; __device__ __forceinline__ void gemm_phase(const u16* __restrict__ A, const u16* __restrict__ Bt, const GemmEpi ep, int wv) {
;     ...
;     if constexpr (EPI == EPI_SWIGLU) {
;       u16* out = reinterpret_cast<u16*>(ep.out0);
;       UNR for (int ai = 0; ai < 2; ++ai) UNR for (int m = 0; m < 4; ++m) {
;         const int rl0 = ai * HALF + wr * 64 + m * 16 + fq * 4;
;         const f32x4 r4 = *reinterpret_cast<const f32x4*>(lrs + rl0);
;         UNR for (int j = 0; j < 4; ++j) {
;           const int row = brow + rl0 + j;
;           const float rs = r4[j], ce = -1.4426950408889634f * rs, r2 = rs * rs;
;           UNR for (int n = 0; n < 2; ++n) {
;             const int col = (bcol >> 1) + wc * 32 + n * 16 + fr;
;             const float g = acc[ai][0][m][n][j], u = acc[ai][1][m][n][j];
;             const float sg = __builtin_amdgcn_rcpf(1.f + __builtin_amdgcn_exp2f(ce * g));
;             out[(size_t)row * ep.ldc + col] = f2bf((g * u) * (r2 * sg));
;           }
;         }
;       }
	v_rcp_f32_e32 v86, v86
	v_rcp_f32_e32 v87, v87
	v_mul_f32_e32 v86, v149, v86
	v_mul_f32_e32 v87, v149, v87
	v_mul_f32_e32 v94, v94, v86
	v_mul_f32_e32 v95, v95, v87
	v_cvt_pk_bf16_f32 v85, v94, v95
	v_mul_f32_e32 v88, v80, v88
	v_mul_f32_e32 v89, v81, v89
	v_mul_f32_e32 v80, v135, v80
	v_mul_f32_e32 v81, v135, v81
	v_exp_f32_e32 v80, v80
	v_exp_f32_e32 v81, v81
	v_add_f32_e32 v80, 1.0, v80
	v_add_f32_e32 v81, 1.0, v81
	v_rcp_f32_e32 v80, v80
	v_rcp_f32_e32 v81, v81
	v_mul_f32_e32 v80, v149, v80
	v_mul_f32_e32 v81, v149, v81
	v_mul_f32_e32 v88, v88, v80
	v_mul_f32_e32 v89, v89, v81
	v_cvt_pk_bf16_f32 v86, v88, v89
	v_mul_f32_e32 v90, v82, v90
	v_mul_f32_e32 v91, v83, v91
	v_mul_f32_e32 v82, v135, v82
	v_mul_f32_e32 v83, v135, v83
	v_exp_f32_e32 v82, v82
	v_exp_f32_e32 v83, v83
	v_add_f32_e32 v82, 1.0, v82
	v_add_f32_e32 v83, 1.0, v83
	v_rcp_f32_e32 v82, v82
	v_rcp_f32_e32 v83, v83
	v_mul_f32_e32 v82, v149, v82
	v_mul_f32_e32 v83, v149, v83
	v_mul_f32_e32 v90, v90, v82
	v_mul_f32_e32 v91, v91, v83
	v_cvt_pk_bf16_f32 v87, v90, v91
	s_nop 1
	v_permlane16_swap_b32_e32 v84, v86
	v_permlane16_swap_b32_e32 v85, v87
	global_store_dwordx4 v134, v[84:87], s[10:11]
	v_add_u32_e32 v134, 0x81000, v132
	v_mul_f32_e32 v135, 0xbfb8aa3b, v153
	v_mul_f32_e32 v149, v153, v153
	ds_read_b32 v153, v133 offset:704
	v_mul_f32_e32 v76, v68, v76
	v_mul_f32_e32 v77, v69, v77
	v_mul_f32_e32 v68, v135, v68
	v_mul_f32_e32 v69, v135, v69
	v_exp_f32_e32 v68, v68
	v_exp_f32_e32 v69, v69
	v_add_f32_e32 v68, 1.0, v68
	v_add_f32_e32 v69, 1.0, v69
	v_rcp_f32_e32 v68, v68
	v_rcp_f32_e32 v69, v69
	v_mul_f32_e32 v68, v149, v68
	v_mul_f32_e32 v69, v149, v69
	v_mul_f32_e32 v76, v76, v68
	v_mul_f32_e32 v77, v77, v69
	v_cvt_pk_bf16_f32 v68, v76, v77
	v_mul_f32_e32 v78, v70, v78
	v_mul_f32_e32 v79, v71, v79
	v_mul_f32_e32 v70, v135, v70
	v_mul_f32_e32 v71, v135, v71
	v_exp_f32_e32 v70, v70
	v_exp_f32_e32 v71, v71
	v_add_f32_e32 v70, 1.0, v70
	v_add_f32_e32 v71, 1.0, v71
	v_rcp_f32_e32 v70, v70
	v_rcp_f32_e32 v71, v71
	v_mul_f32_e32 v70, v149, v70
	v_mul_f32_e32 v71, v149, v71
	v_mul_f32_e32 v78, v78, v70
	v_mul_f32_e32 v79, v79, v71
	v_cvt_pk_bf16_f32 v69, v78, v79
	v_mul_f32_e32 v72, v64, v72
	v_mul_f32_e32 v73, v65, v73
	v_mul_f32_e32 v64, v135, v64
	v_mul_f32_e32 v65, v135, v65
	v_exp_f32_e32 v64, v64
	v_exp_f32_e32 v65, v65
	v_add_f32_e32 v64, 1.0, v64
	v_add_f32_e32 v65, 1.0, v65
	v_rcp_f32_e32 v64, v64
	v_rcp_f32_e32 v65, v65
	v_mul_f32_e32 v64, v149, v64
	v_mul_f32_e32 v65, v149, v65
	v_mul_f32_e32 v72, v72, v64
	v_mul_f32_e32 v73, v73, v65
	v_cvt_pk_bf16_f32 v70, v72, v73
	v_mul_f32_e32 v74, v66, v74
	v_mul_f32_e32 v75, v67, v75
	v_mul_f32_e32 v66, v135, v66
	v_mul_f32_e32 v67, v135, v67
	v_exp_f32_e32 v66, v66
	v_exp_f32_e32 v67, v67
	v_add_f32_e32 v66, 1.0, v66
	v_add_f32_e32 v67, 1.0, v67
	v_rcp_f32_e32 v66, v66
	v_rcp_f32_e32 v67, v67
	v_mul_f32_e32 v66, v149, v66
	v_mul_f32_e32 v67, v149, v67
	v_mul_f32_e32 v74, v74, v66
	v_mul_f32_e32 v75, v75, v67
	v_cvt_pk_bf16_f32 v71, v74, v75
	s_nop 1
	v_permlane16_swap_b32_e32 v68, v70
	v_permlane16_swap_b32_e32 v69, v71
	global_store_dwordx4 v134, v[68:71], s[10:11]
	s_waitcnt lgkmcnt(0)
	v_add_u32_e32 v134, 0x158000, v132
	v_mul_f32_e32 v135, 0xbfb8aa3b, v150
	v_mul_f32_e32 v149, v150, v150
	v_mul_f32_e32 v60, v52, v60
	v_mul_f32_e32 v61, v53, v61
	v_mul_f32_e32 v52, v135, v52
	v_mul_f32_e32 v53, v135, v53
	v_exp_f32_e32 v52, v52
	v_exp_f32_e32 v53, v53
	v_add_f32_e32 v52, 1.0, v52
	v_add_f32_e32 v53, 1.0, v53
	v_rcp_f32_e32 v52, v52
	v_rcp_f32_e32 v53, v53
	v_mul_f32_e32 v52, v149, v52
	v_mul_f32_e32 v53, v149, v53
	v_mul_f32_e32 v60, v60, v52
	v_mul_f32_e32 v61, v61, v53
	v_cvt_pk_bf16_f32 v52, v60, v61
	v_mul_f32_e32 v62, v54, v62
	v_mul_f32_e32 v63, v55, v63
	v_mul_f32_e32 v54, v135, v54
	v_mul_f32_e32 v55, v135, v55
	v_exp_f32_e32 v54, v54
	v_exp_f32_e32 v55, v55
	v_add_f32_e32 v54, 1.0, v54
	v_add_f32_e32 v55, 1.0, v55
	v_rcp_f32_e32 v54, v54
	v_rcp_f32_e32 v55, v55
	v_mul_f32_e32 v54, v149, v54
	v_mul_f32_e32 v55, v149, v55
	v_mul_f32_e32 v62, v62, v54
	v_mul_f32_e32 v63, v63, v55
	v_cvt_pk_bf16_f32 v53, v62, v63
	v_mul_f32_e32 v56, v48, v56
	v_mul_f32_e32 v57, v49, v57
	v_mul_f32_e32 v48, v135, v48
	v_mul_f32_e32 v49, v135, v49
	v_exp_f32_e32 v48, v48
	v_exp_f32_e32 v49, v49
	v_add_f32_e32 v48, 1.0, v48
	v_add_f32_e32 v49, 1.0, v49
	v_rcp_f32_e32 v48, v48
	v_rcp_f32_e32 v49, v49
	v_mul_f32_e32 v48, v149, v48
	v_mul_f32_e32 v49, v149, v49
	v_mul_f32_e32 v56, v56, v48
	v_mul_f32_e32 v57, v57, v49
	v_cvt_pk_bf16_f32 v54, v56, v57
	v_mul_f32_e32 v58, v50, v58
	v_mul_f32_e32 v59, v51, v59
	v_mul_f32_e32 v50, v135, v50
	v_mul_f32_e32 v51, v135, v51
	v_exp_f32_e32 v50, v50
	v_exp_f32_e32 v51, v51
	v_add_f32_e32 v50, 1.0, v50
	v_add_f32_e32 v51, 1.0, v51
	v_rcp_f32_e32 v50, v50
	v_rcp_f32_e32 v51, v51
	v_mul_f32_e32 v50, v149, v50
	v_mul_f32_e32 v51, v149, v51
	v_mul_f32_e32 v58, v58, v50
	v_mul_f32_e32 v59, v59, v51
	v_cvt_pk_bf16_f32 v55, v58, v59
	s_nop 1
	v_permlane16_swap_b32_e32 v52, v54
	v_permlane16_swap_b32_e32 v53, v55
	global_store_dwordx4 v134, v[52:55], s[10:11]
	v_add_u32_e32 v134, 0x183000, v132
	v_mul_f32_e32 v135, 0xbfb8aa3b, v151
	v_mul_f32_e32 v149, v151, v151
	v_mul_f32_e32 v44, v36, v44
	v_mul_f32_e32 v45, v37, v45
	v_mul_f32_e32 v36, v135, v36
	v_mul_f32_e32 v37, v135, v37
	v_exp_f32_e32 v36, v36
	v_exp_f32_e32 v37, v37
	v_add_f32_e32 v36, 1.0, v36
	v_add_f32_e32 v37, 1.0, v37
	v_rcp_f32_e32 v36, v36
	v_rcp_f32_e32 v37, v37
	v_mul_f32_e32 v36, v149, v36
	v_mul_f32_e32 v37, v149, v37
	v_mul_f32_e32 v44, v44, v36
	v_mul_f32_e32 v45, v45, v37
	v_cvt_pk_bf16_f32 v36, v44, v45
	v_mul_f32_e32 v46, v38, v46
; __device__ __forceinline__ u16 f2bf(float x) { return (u16)(cvtpk(x, x) & 0xffffu); }
; #define UNR _Pragma("unroll")
; #define WAIT_V(n) asm volatile("s_waitcnt vmcnt(" #n ")" ::: "memory")
; template <int EPI, int lda, int ldb, int N, int K>
; __device__ __forceinline__ void gemm_phase(const u16* __restrict__ A, const u16* __restrict__ Bt, const GemmEpi ep, int wv) {
;     ...
;     if constexpr (EPI == EPI_SWIGLU) {
;       u16* out = reinterpret_cast<u16*>(ep.out0);
;       UNR for (int ai = 0; ai < 2; ++ai) UNR for (int m = 0; m < 4; ++m) {
;         const int rl0 = ai * HALF + wr * 64 + m * 16 + fq * 4;
;         const f32x4 r4 = *reinterpret_cast<const f32x4*>(lrs + rl0);
;         UNR for (int j = 0; j < 4; ++j) {
;           const int row = brow + rl0 + j;
;           const float rs = r4[j], ce = -1.4426950408889634f * rs, r2 = rs * rs;
;           UNR for (int n = 0; n < 2; ++n) {
;             const int col = (bcol >> 1) + wc * 32 + n * 16 + fr;
;             const float g = acc[ai][0][m][n][j], u = acc[ai][1][m][n][j];
;             const float sg = __builtin_amdgcn_rcpf(1.f + __builtin_amdgcn_exp2f(ce * g));
;             out[(size_t)row * ep.ldc + col] = f2bf((g * u) * (r2 * sg));
;           }
;         }
;       }
;     ...
;     if constexpr (PF) {
;       WAIT_V(0);
;       __syncthreads();
;       if constexpr (CONS) { if (more && tidx < 256) { float sq = 0.f; UNR for (int pp = 0; pp < 8; ++pp) sq += nss[pp];
;         lrs[tidx] = rsqrtf(sq * (1.f / DM) + 1e-6f); } }
;       if (!more) break;
	v_mul_f32_e32 v47, v39, v47
	v_mul_f32_e32 v38, v135, v38
	v_mul_f32_e32 v39, v135, v39
	v_exp_f32_e32 v38, v38
	v_exp_f32_e32 v39, v39
	v_add_f32_e32 v38, 1.0, v38
	v_add_f32_e32 v39, 1.0, v39
	v_rcp_f32_e32 v38, v38
	v_rcp_f32_e32 v39, v39
	v_mul_f32_e32 v38, v149, v38
	v_mul_f32_e32 v39, v149, v39
	v_mul_f32_e32 v46, v46, v38
	v_mul_f32_e32 v47, v47, v39
	v_cvt_pk_bf16_f32 v37, v46, v47
	v_mul_f32_e32 v40, v32, v40
	v_mul_f32_e32 v41, v33, v41
	v_mul_f32_e32 v32, v135, v32
	v_mul_f32_e32 v33, v135, v33
	v_exp_f32_e32 v32, v32
	v_exp_f32_e32 v33, v33
	v_add_f32_e32 v32, 1.0, v32
	v_add_f32_e32 v33, 1.0, v33
	v_rcp_f32_e32 v32, v32
	v_rcp_f32_e32 v33, v33
	v_mul_f32_e32 v32, v149, v32
	v_mul_f32_e32 v33, v149, v33
	v_mul_f32_e32 v40, v40, v32
	v_mul_f32_e32 v41, v41, v33
	v_cvt_pk_bf16_f32 v38, v40, v41
	v_mul_f32_e32 v42, v34, v42
	v_mul_f32_e32 v43, v35, v43
	v_mul_f32_e32 v34, v135, v34
	v_mul_f32_e32 v35, v135, v35
	v_exp_f32_e32 v34, v34
	v_exp_f32_e32 v35, v35
	v_add_f32_e32 v34, 1.0, v34
	v_add_f32_e32 v35, 1.0, v35
	v_rcp_f32_e32 v34, v34
	v_rcp_f32_e32 v35, v35
	v_mul_f32_e32 v34, v149, v34
	v_mul_f32_e32 v35, v149, v35
	v_mul_f32_e32 v42, v42, v34
	v_mul_f32_e32 v43, v43, v35
	v_cvt_pk_bf16_f32 v39, v42, v43
	s_nop 1
	v_permlane16_swap_b32_e32 v36, v38
	v_permlane16_swap_b32_e32 v37, v39
	global_store_dwordx4 v134, v[36:39], s[10:11]
	v_add_u32_e32 v134, 0x1ae000, v132
	v_mul_f32_e32 v135, 0xbfb8aa3b, v152
	v_mul_f32_e32 v149, v152, v152
	v_mul_f32_e32 v28, v20, v28
	v_mul_f32_e32 v29, v21, v29
	v_mul_f32_e32 v20, v135, v20
	v_mul_f32_e32 v21, v135, v21
	v_exp_f32_e32 v20, v20
	v_exp_f32_e32 v21, v21
	v_add_f32_e32 v20, 1.0, v20
	v_add_f32_e32 v21, 1.0, v21
	v_rcp_f32_e32 v20, v20
	v_rcp_f32_e32 v21, v21
	v_mul_f32_e32 v20, v149, v20
	v_mul_f32_e32 v21, v149, v21
	v_mul_f32_e32 v28, v28, v20
	v_mul_f32_e32 v29, v29, v21
	v_cvt_pk_bf16_f32 v20, v28, v29
	v_mul_f32_e32 v30, v22, v30
	v_mul_f32_e32 v31, v23, v31
	v_mul_f32_e32 v22, v135, v22
	v_mul_f32_e32 v23, v135, v23
	v_exp_f32_e32 v22, v22
	v_exp_f32_e32 v23, v23
	v_add_f32_e32 v22, 1.0, v22
	v_add_f32_e32 v23, 1.0, v23
	v_rcp_f32_e32 v22, v22
	v_rcp_f32_e32 v23, v23
	v_mul_f32_e32 v22, v149, v22
	v_mul_f32_e32 v23, v149, v23
	v_mul_f32_e32 v30, v30, v22
	v_mul_f32_e32 v31, v31, v23
	v_cvt_pk_bf16_f32 v21, v30, v31
	v_mul_f32_e32 v24, v16, v24
	v_mul_f32_e32 v25, v17, v25
	v_mul_f32_e32 v16, v135, v16
	v_mul_f32_e32 v17, v135, v17
	v_exp_f32_e32 v16, v16
	v_exp_f32_e32 v17, v17
	v_add_f32_e32 v16, 1.0, v16
	v_add_f32_e32 v17, 1.0, v17
	v_rcp_f32_e32 v16, v16
	v_rcp_f32_e32 v17, v17
	v_mul_f32_e32 v16, v149, v16
	v_mul_f32_e32 v17, v149, v17
	v_mul_f32_e32 v24, v24, v16
	v_mul_f32_e32 v25, v25, v17
	v_cvt_pk_bf16_f32 v22, v24, v25
	v_mul_f32_e32 v26, v18, v26
	v_mul_f32_e32 v27, v19, v27
	v_mul_f32_e32 v18, v135, v18
	v_mul_f32_e32 v19, v135, v19
	v_exp_f32_e32 v18, v18
	v_exp_f32_e32 v19, v19
	v_add_f32_e32 v18, 1.0, v18
	v_add_f32_e32 v19, 1.0, v19
	v_rcp_f32_e32 v18, v18
	v_rcp_f32_e32 v19, v19
	v_mul_f32_e32 v18, v149, v18
	v_mul_f32_e32 v19, v149, v19
	v_mul_f32_e32 v26, v26, v18
	v_mul_f32_e32 v27, v27, v19
	v_cvt_pk_bf16_f32 v23, v26, v27
	s_nop 1
	v_permlane16_swap_b32_e32 v20, v22
	v_permlane16_swap_b32_e32 v21, v23
	global_store_dwordx4 v134, v[20:23], s[10:11]
	v_add_u32_e32 v134, 0x1d9000, v132
	v_mul_f32_e32 v135, 0xbfb8aa3b, v153
	v_mul_f32_e32 v149, v153, v153
	v_mul_f32_e32 v12, v4, v12
	v_mul_f32_e32 v13, v5, v13
	v_mul_f32_e32 v4, v135, v4
	v_mul_f32_e32 v5, v135, v5
	v_exp_f32_e32 v4, v4
	v_exp_f32_e32 v5, v5
	v_add_f32_e32 v4, 1.0, v4
	v_add_f32_e32 v5, 1.0, v5
	v_rcp_f32_e32 v4, v4
	v_rcp_f32_e32 v5, v5
	v_mul_f32_e32 v4, v149, v4
	v_mul_f32_e32 v5, v149, v5
	v_mul_f32_e32 v12, v12, v4
	v_mul_f32_e32 v13, v13, v5
	v_cvt_pk_bf16_f32 v4, v12, v13
	v_mul_f32_e32 v14, v6, v14
	v_mul_f32_e32 v15, v7, v15
	v_mul_f32_e32 v6, v135, v6
	v_mul_f32_e32 v7, v135, v7
	v_exp_f32_e32 v6, v6
	v_exp_f32_e32 v7, v7
	v_add_f32_e32 v6, 1.0, v6
	v_add_f32_e32 v7, 1.0, v7
	v_rcp_f32_e32 v6, v6
	v_rcp_f32_e32 v7, v7
	v_mul_f32_e32 v6, v149, v6
	v_mul_f32_e32 v7, v149, v7
	v_mul_f32_e32 v14, v14, v6
	v_mul_f32_e32 v15, v15, v7
	v_cvt_pk_bf16_f32 v5, v14, v15
	v_mul_f32_e32 v8, v0, v8
	v_mul_f32_e32 v9, v1, v9
	v_mul_f32_e32 v0, v135, v0
	v_mul_f32_e32 v1, v135, v1
	v_exp_f32_e32 v0, v0
	v_exp_f32_e32 v1, v1
	v_add_f32_e32 v0, 1.0, v0
	v_add_f32_e32 v1, 1.0, v1
	v_rcp_f32_e32 v0, v0
	v_rcp_f32_e32 v1, v1
	v_mul_f32_e32 v0, v149, v0
	v_mul_f32_e32 v1, v149, v1
	v_mul_f32_e32 v8, v8, v0
	v_mul_f32_e32 v9, v9, v1
	v_cvt_pk_bf16_f32 v6, v8, v9
	v_mul_f32_e32 v10, v2, v10
	v_mul_f32_e32 v11, v3, v11
	v_mul_f32_e32 v2, v135, v2
	v_mul_f32_e32 v3, v135, v3
	v_exp_f32_e32 v2, v2
	v_exp_f32_e32 v3, v3
	v_add_f32_e32 v2, 1.0, v2
	v_add_f32_e32 v3, 1.0, v3
	v_rcp_f32_e32 v2, v2
	v_rcp_f32_e32 v3, v3
	v_mul_f32_e32 v2, v149, v2
	v_mul_f32_e32 v3, v149, v3
	v_mul_f32_e32 v10, v10, v2
	v_mul_f32_e32 v11, v11, v3
	v_cvt_pk_bf16_f32 v7, v10, v11
	s_nop 1
	v_permlane16_swap_b32_e32 v4, v6
	v_permlane16_swap_b32_e32 v5, v7
	global_store_dwordx4 v134, v[4:7], s[10:11]
	s_waitcnt vmcnt(8)
	s_waitcnt vmcnt(8)
	v_add_f32_e32 v148, 0, v131
	s_barrier
	s_and_saveexec_b64 s[38:39], s[44:45]
	s_cbranch_execz .LBB0_1560
	v_add_f32_e32 v0, v141, v148
	v_add_f32_e32 v0, v140, v0
	v_add_f32_e32 v0, v139, v0
	v_add_f32_e32 v0, v138, v0
	v_add_f32_e32 v0, v137, v0
	v_add_f32_e32 v0, v136, v0
	v_add_f32_e32 v0, v128, v0
	v_fmamk_f32 v0, v0, 0x3a000000, v143
	v_mul_f32_e32 v1, 0x4b800000, v0
	v_cmp_gt_f32_e32 vcc, s61, v0
	s_nop 1
	v_cndmask_b32_e32 v0, v0, v1, vcc
	v_rsq_f32_e32 v0, v0
	v_lshl_add_u32 v1, v130, 2, 0
	v_add_u32_e32 v1, 0x20000, v1
	v_mul_f32_e32 v2, 0x45800000, v0
	v_cndmask_b32_e32 v0, v0, v2, vcc
	ds_write_b32 v1, v0
	s_branch .LBB0_1560
